# GEMM loops: address/m0 prefix of each load segment issued before the block-closing barrier, between the last MFMAs (10 segments, 31 instructions)
# baseline (speedup 1.0000x reference)
.LBB0_177:
	ds_read_b128 v[128:131], v171
	ds_read_b128 v[132:135], v171 offset:1024
	ds_read_b128 v[136:139], v171 offset:2048
	ds_read_b128 v[160:163], v171 offset:3072
	ds_read_b128 v[164:167], v172
	ds_read_b128 v[174:177], v172 offset:1024
	ds_read_b128 v[178:181], v172 offset:2048
	ds_read_b128 v[182:185], v172 offset:3072
	s_add_u32 s52, s44, 0xfffc0080
	s_addc_u32 s53, s45, -1
	s_cmp_eq_u32 s84, 12
	s_cselect_b32 s57, s7, s53
	s_cselect_b32 s56, s8, s52
	s_cselect_b32 s53, s27, s83
	s_cselect_b32 s52, s29, s43
	v_lshl_add_u64 v[198:199], s[44:45], 0, v[152:153]
	s_add_i32 m0, s33, 0xc000
	ds_read_b128 v[186:189], v173
	ds_read_b128 v[190:193], v173 offset:1024
	ds_read_b128 v[194:197], v173 offset:2048
	ds_read_b128 v[202:205], v173 offset:3072
	ds_read_b128 v[206:209], v173 offset:4096
	ds_read_b128 v[210:213], v173 offset:5120
	ds_read_b128 v[214:217], v173 offset:6144
	ds_read_b128 v[218:221], v173 offset:7168
	global_load_lds_dwordx4 v[198:199], off
	s_add_i32 m0, s33, 0xe000
	v_lshl_add_u64 v[198:199], s[44:45], 0, v[154:155]
	global_load_lds_dwordx4 v[198:199], off
	s_waitcnt vmcnt(8)
	s_waitcnt lgkmcnt(0)
	s_barrier
	s_waitcnt lgkmcnt(0)
	v_mfma_f32_16x16x32_bf16 v[124:127], v[128:131], v[186:189], v[124:127]
	v_mfma_f32_16x16x32_bf16 v[120:123], v[136:139], v[186:189], v[120:123]
	v_mfma_f32_16x16x32_bf16 v[112:115], v[128:131], v[194:197], v[112:115]
	v_mfma_f32_16x16x32_bf16 v[104:107], v[136:139], v[194:197], v[104:107]
	v_mfma_f32_16x16x32_bf16 v[100:103], v[128:131], v[206:209], v[100:103]
	v_mfma_f32_16x16x32_bf16 v[92:95], v[136:139], v[206:209], v[92:95]
	v_mfma_f32_16x16x32_bf16 v[84:87], v[128:131], v[214:217], v[84:87]
	v_mfma_f32_16x16x32_bf16 v[76:79], v[136:139], v[214:217], v[76:79]
	v_mfma_f32_16x16x32_bf16 v[124:127], v[132:135], v[190:193], v[124:127]
	v_mfma_f32_16x16x32_bf16 v[120:123], v[160:163], v[190:193], v[120:123]
	v_mfma_f32_16x16x32_bf16 v[112:115], v[132:135], v[202:205], v[112:115]
	v_mfma_f32_16x16x32_bf16 v[104:107], v[160:163], v[202:205], v[104:107]
	v_mfma_f32_16x16x32_bf16 v[100:103], v[132:135], v[210:213], v[100:103]
	v_mfma_f32_16x16x32_bf16 v[92:95], v[160:163], v[210:213], v[92:95]
	v_mfma_f32_16x16x32_bf16 v[84:87], v[132:135], v[218:221], v[84:87]
	v_mfma_f32_16x16x32_bf16 v[76:79], v[160:163], v[218:221], v[76:79]
	v_mfma_f32_16x16x32_bf16 v[116:119], v[164:167], v[186:189], v[116:119]
	v_mfma_f32_16x16x32_bf16 v[108:111], v[178:181], v[186:189], v[108:111]
	v_mfma_f32_16x16x32_bf16 v[96:99], v[164:167], v[194:197], v[96:99]
	v_mfma_f32_16x16x32_bf16 v[88:91], v[178:181], v[194:197], v[88:91]
	v_mfma_f32_16x16x32_bf16 v[80:83], v[164:167], v[206:209], v[80:83]
	v_mfma_f32_16x16x32_bf16 v[72:75], v[178:181], v[206:209], v[72:75]
	v_mfma_f32_16x16x32_bf16 v[68:71], v[164:167], v[214:217], v[68:71]
	v_mfma_f32_16x16x32_bf16 v[64:67], v[178:181], v[214:217], v[64:67]
	v_mfma_f32_16x16x32_bf16 v[116:119], v[174:177], v[190:193], v[116:119]
	v_mfma_f32_16x16x32_bf16 v[108:111], v[182:185], v[190:193], v[108:111]
	v_mfma_f32_16x16x32_bf16 v[96:99], v[174:177], v[202:205], v[96:99]
	v_mfma_f32_16x16x32_bf16 v[88:91], v[182:185], v[202:205], v[88:91]
	v_mfma_f32_16x16x32_bf16 v[80:83], v[174:177], v[210:213], v[80:83]
	v_mfma_f32_16x16x32_bf16 v[72:75], v[182:185], v[210:213], v[72:75]
	s_add_i32 s85, s80, s3
	v_lshl_add_u64 v[198:199], s[52:53], 0, v[142:143]
	s_mov_b32 m0, s85
	v_mfma_f32_16x16x32_bf16 v[68:71], v[174:177], v[218:221], v[68:71]
	v_mfma_f32_16x16x32_bf16 v[64:67], v[182:185], v[218:221], v[64:67]
	s_barrier
	ds_read_b128 v[186:189], v173 offset:16384
	ds_read_b128 v[190:193], v173 offset:17408
	ds_read_b128 v[194:197], v173 offset:18432
	ds_read_b128 v[202:205], v173 offset:19456
	ds_read_b128 v[206:209], v173 offset:20480
	ds_read_b128 v[210:213], v173 offset:21504
	ds_read_b128 v[214:217], v173 offset:22528
	ds_read_b128 v[218:221], v173 offset:23552
	global_load_lds_dwordx4 v[198:199], off
	s_add_i32 m0, s85, 0x2000
	s_add_u32 s86, s52, 0x40000
	v_lshl_add_u64 v[200:201], s[52:53], 0, v[146:147]
	s_addc_u32 s87, s53, 0
	s_add_i32 s85, s81, s3
	global_load_lds_dwordx4 v[200:201], off
	v_lshl_add_u64 v[222:223], s[86:87], 0, v[142:143]
	s_mov_b32 m0, s85
	v_lshl_add_u64 v[224:225], s[56:57], 0, v[144:145]
	global_load_lds_dwordx4 v[222:223], off
	s_add_i32 m0, s85, 0x2000
	v_lshl_add_u64 v[222:223], s[86:87], 0, v[146:147]
	global_load_lds_dwordx4 v[222:223], off
	s_mov_b32 m0, s33
	v_lshl_add_u64 v[222:223], s[56:57], 0, v[140:141]
	global_load_lds_dwordx4 v[222:223], off
	s_mov_b32 m0, s62
	s_nop 0
	global_load_lds_dwordx4 v[224:225], off
	s_waitcnt vmcnt(8)
	s_waitcnt lgkmcnt(0)
	s_barrier
	s_waitcnt lgkmcnt(0)
	v_mfma_f32_16x16x32_bf16 v[60:63], v[128:131], v[186:189], v[60:63]
	v_mfma_f32_16x16x32_bf16 v[56:59], v[136:139], v[186:189], v[56:59]
	v_mfma_f32_16x16x32_bf16 v[52:55], v[128:131], v[194:197], v[52:55]
	v_mfma_f32_16x16x32_bf16 v[44:47], v[136:139], v[194:197], v[44:47]
	v_mfma_f32_16x16x32_bf16 v[36:39], v[128:131], v[206:209], v[36:39]
	v_mfma_f32_16x16x32_bf16 v[28:31], v[136:139], v[206:209], v[28:31]
	v_mfma_f32_16x16x32_bf16 v[20:23], v[128:131], v[214:217], v[20:23]
	v_mfma_f32_16x16x32_bf16 v[12:15], v[136:139], v[214:217], v[12:15]
	v_mfma_f32_16x16x32_bf16 v[60:63], v[132:135], v[190:193], v[60:63]
	v_mfma_f32_16x16x32_bf16 v[56:59], v[160:163], v[190:193], v[56:59]
	v_mfma_f32_16x16x32_bf16 v[52:55], v[132:135], v[202:205], v[52:55]
	v_mfma_f32_16x16x32_bf16 v[44:47], v[160:163], v[202:205], v[44:47]
	v_mfma_f32_16x16x32_bf16 v[36:39], v[132:135], v[210:213], v[36:39]
	v_mfma_f32_16x16x32_bf16 v[28:31], v[160:163], v[210:213], v[28:31]
	v_mfma_f32_16x16x32_bf16 v[20:23], v[132:135], v[218:221], v[20:23]
	v_mfma_f32_16x16x32_bf16 v[12:15], v[160:163], v[218:221], v[12:15]
	v_mfma_f32_16x16x32_bf16 v[48:51], v[164:167], v[186:189], v[48:51]
	v_mfma_f32_16x16x32_bf16 v[40:43], v[178:181], v[186:189], v[40:43]
	v_mfma_f32_16x16x32_bf16 v[32:35], v[164:167], v[194:197], v[32:35]
	v_mfma_f32_16x16x32_bf16 v[24:27], v[178:181], v[194:197], v[24:27]
	v_mfma_f32_16x16x32_bf16 v[16:19], v[164:167], v[206:209], v[16:19]
	v_mfma_f32_16x16x32_bf16 v[8:11], v[178:181], v[206:209], v[8:11]
	v_mfma_f32_16x16x32_bf16 v[4:7], v[164:167], v[214:217], v[4:7]
	v_mfma_f32_16x16x32_bf16 v[0:3], v[178:181], v[214:217], v[0:3]
	v_mfma_f32_16x16x32_bf16 v[48:51], v[174:177], v[190:193], v[48:51]
	v_mfma_f32_16x16x32_bf16 v[40:43], v[182:185], v[190:193], v[40:43]
	v_mfma_f32_16x16x32_bf16 v[32:35], v[174:177], v[202:205], v[32:35]
	v_mfma_f32_16x16x32_bf16 v[24:27], v[182:185], v[202:205], v[24:27]
	v_mfma_f32_16x16x32_bf16 v[16:19], v[174:177], v[210:213], v[16:19]
	v_mfma_f32_16x16x32_bf16 v[8:11], v[182:185], v[210:213], v[8:11]
	s_add_i32 s85, 0, 0x18000
	v_add_u32_e32 v148, s85, v169
	s_add_i32 s86, 0, 0x1c000
	v_mfma_f32_16x16x32_bf16 v[4:7], v[174:177], v[218:221], v[4:7]
	v_mfma_f32_16x16x32_bf16 v[0:3], v[182:185], v[218:221], v[0:3]
	s_barrier
	ds_read_b128 v[128:131], v148
	ds_read_b128 v[132:135], v148 offset:1024
	ds_read_b128 v[136:139], v148 offset:2048
	ds_read_b128 v[160:163], v148 offset:3072
	v_add_u32_e32 v148, s86, v169
	ds_read_b128 v[164:167], v148
	ds_read_b128 v[174:177], v148 offset:1024
	ds_read_b128 v[178:181], v148 offset:2048
	ds_read_b128 v[182:185], v148 offset:3072
	s_add_u32 s56, s56, 0x40000
	s_addc_u32 s57, s57, 0
	s_mov_b32 m0, s63
	v_lshl_add_u64 v[226:227], s[56:57], 0, v[140:141]
	ds_read_b128 v[186:189], v173 offset:32768
	ds_read_b128 v[190:193], v173 offset:33792
	ds_read_b128 v[194:197], v173 offset:34816
	ds_read_b128 v[202:205], v173 offset:35840
	ds_read_b128 v[206:209], v173 offset:36864
	ds_read_b128 v[210:213], v173 offset:37888
	ds_read_b128 v[214:217], v173 offset:38912
	ds_read_b128 v[218:221], v173 offset:39936
	global_load_lds_dwordx4 v[226:227], off
	s_mov_b32 m0, s64
	v_lshl_add_u64 v[226:227], s[56:57], 0, v[144:145]
	global_load_lds_dwordx4 v[226:227], off
	s_waitcnt vmcnt(8)
	s_waitcnt lgkmcnt(0)
	s_barrier
	s_waitcnt lgkmcnt(0)
	v_mfma_f32_16x16x32_bf16 v[124:127], v[128:131], v[186:189], v[124:127]
	v_mfma_f32_16x16x32_bf16 v[120:123], v[136:139], v[186:189], v[120:123]
	v_mfma_f32_16x16x32_bf16 v[112:115], v[128:131], v[194:197], v[112:115]
	v_mfma_f32_16x16x32_bf16 v[104:107], v[136:139], v[194:197], v[104:107]
	v_mfma_f32_16x16x32_bf16 v[100:103], v[128:131], v[206:209], v[100:103]
	v_mfma_f32_16x16x32_bf16 v[92:95], v[136:139], v[206:209], v[92:95]
	v_mfma_f32_16x16x32_bf16 v[84:87], v[128:131], v[214:217], v[84:87]
	v_mfma_f32_16x16x32_bf16 v[76:79], v[136:139], v[214:217], v[76:79]
	v_mfma_f32_16x16x32_bf16 v[124:127], v[132:135], v[190:193], v[124:127]
	v_mfma_f32_16x16x32_bf16 v[120:123], v[160:163], v[190:193], v[120:123]
	v_mfma_f32_16x16x32_bf16 v[112:115], v[132:135], v[202:205], v[112:115]
	v_mfma_f32_16x16x32_bf16 v[104:107], v[160:163], v[202:205], v[104:107]
	v_mfma_f32_16x16x32_bf16 v[100:103], v[132:135], v[210:213], v[100:103]
	v_mfma_f32_16x16x32_bf16 v[92:95], v[160:163], v[210:213], v[92:95]
	v_mfma_f32_16x16x32_bf16 v[84:87], v[132:135], v[218:221], v[84:87]
	v_mfma_f32_16x16x32_bf16 v[76:79], v[160:163], v[218:221], v[76:79]
	v_mfma_f32_16x16x32_bf16 v[116:119], v[164:167], v[186:189], v[116:119]
	v_mfma_f32_16x16x32_bf16 v[108:111], v[178:181], v[186:189], v[108:111]
	v_mfma_f32_16x16x32_bf16 v[96:99], v[164:167], v[194:197], v[96:99]
	v_mfma_f32_16x16x32_bf16 v[88:91], v[178:181], v[194:197], v[88:91]
	v_mfma_f32_16x16x32_bf16 v[80:83], v[164:167], v[206:209], v[80:83]
	v_mfma_f32_16x16x32_bf16 v[72:75], v[178:181], v[206:209], v[72:75]
	v_mfma_f32_16x16x32_bf16 v[68:71], v[164:167], v[214:217], v[68:71]
	v_mfma_f32_16x16x32_bf16 v[64:67], v[178:181], v[214:217], v[64:67]
	v_mfma_f32_16x16x32_bf16 v[116:119], v[174:177], v[190:193], v[116:119]
	v_mfma_f32_16x16x32_bf16 v[108:111], v[182:185], v[190:193], v[108:111]
	v_mfma_f32_16x16x32_bf16 v[96:99], v[174:177], v[202:205], v[96:99]
	v_mfma_f32_16x16x32_bf16 v[88:91], v[182:185], v[202:205], v[88:91]
	v_mfma_f32_16x16x32_bf16 v[80:83], v[174:177], v[210:213], v[80:83]
	v_mfma_f32_16x16x32_bf16 v[72:75], v[182:185], v[210:213], v[72:75]
	s_add_i32 s56, s85, s3
	v_lshl_add_u64 v[198:199], v[198:199], 0, s[16:17]
	s_mov_b32 m0, s56
	v_mfma_f32_16x16x32_bf16 v[68:71], v[174:177], v[218:221], v[68:71]
	v_mfma_f32_16x16x32_bf16 v[64:67], v[182:185], v[218:221], v[64:67]
	s_barrier
	ds_read_b128 v[186:189], v173 offset:49152
	ds_read_b128 v[190:193], v173 offset:50176
	ds_read_b128 v[194:197], v173 offset:51200
	ds_read_b128 v[202:205], v173 offset:52224
	ds_read_b128 v[206:209], v173 offset:53248
	ds_read_b128 v[210:213], v173 offset:54272
	ds_read_b128 v[214:217], v173 offset:55296
	ds_read_b128 v[218:221], v173 offset:56320
	global_load_lds_dwordx4 v[198:199], off
	s_add_i32 m0, s56, 0x2000
	s_add_u32 s52, s52, 0x40080
	v_lshl_add_u64 v[198:199], v[200:201], 0, s[16:17]
	s_addc_u32 s53, s53, 0
	s_add_i32 s56, s86, s3
	global_load_lds_dwordx4 v[198:199], off
	s_mov_b32 m0, s56
	v_lshl_add_u64 v[198:199], s[52:53], 0, v[142:143]
	global_load_lds_dwordx4 v[198:199], off
	s_add_i32 m0, s56, 0x2000
	v_lshl_add_u64 v[198:199], s[52:53], 0, v[146:147]
	global_load_lds_dwordx4 v[198:199], off
	s_mov_b32 m0, s69
	v_lshl_add_u64 v[198:199], v[222:223], 0, s[16:17]
	global_load_lds_dwordx4 v[198:199], off
	s_mov_b32 m0, s72
	v_lshl_add_u64 v[198:199], v[224:225], 0, s[16:17]
	global_load_lds_dwordx4 v[198:199], off
	s_waitcnt vmcnt(8)
	s_waitcnt lgkmcnt(0)
	s_barrier
	s_waitcnt lgkmcnt(0)
	v_mfma_f32_16x16x32_bf16 v[60:63], v[128:131], v[186:189], v[60:63]
	v_mfma_f32_16x16x32_bf16 v[56:59], v[136:139], v[186:189], v[56:59]
	v_mfma_f32_16x16x32_bf16 v[52:55], v[128:131], v[194:197], v[52:55]
	v_mfma_f32_16x16x32_bf16 v[44:47], v[136:139], v[194:197], v[44:47]
	v_mfma_f32_16x16x32_bf16 v[36:39], v[128:131], v[206:209], v[36:39]
	v_mfma_f32_16x16x32_bf16 v[28:31], v[136:139], v[206:209], v[28:31]
	v_mfma_f32_16x16x32_bf16 v[20:23], v[128:131], v[214:217], v[20:23]
	v_mfma_f32_16x16x32_bf16 v[12:15], v[136:139], v[214:217], v[12:15]
	v_mfma_f32_16x16x32_bf16 v[60:63], v[132:135], v[190:193], v[60:63]
	v_mfma_f32_16x16x32_bf16 v[56:59], v[160:163], v[190:193], v[56:59]
	v_mfma_f32_16x16x32_bf16 v[52:55], v[132:135], v[202:205], v[52:55]
	v_mfma_f32_16x16x32_bf16 v[44:47], v[160:163], v[202:205], v[44:47]
	v_mfma_f32_16x16x32_bf16 v[36:39], v[132:135], v[210:213], v[36:39]
	v_mfma_f32_16x16x32_bf16 v[28:31], v[160:163], v[210:213], v[28:31]
	v_mfma_f32_16x16x32_bf16 v[20:23], v[132:135], v[218:221], v[20:23]
	v_mfma_f32_16x16x32_bf16 v[12:15], v[160:163], v[218:221], v[12:15]
	v_mfma_f32_16x16x32_bf16 v[48:51], v[164:167], v[186:189], v[48:51]
	v_mfma_f32_16x16x32_bf16 v[40:43], v[178:181], v[186:189], v[40:43]
	v_mfma_f32_16x16x32_bf16 v[32:35], v[164:167], v[194:197], v[32:35]
	v_mfma_f32_16x16x32_bf16 v[24:27], v[178:181], v[194:197], v[24:27]
	v_mfma_f32_16x16x32_bf16 v[16:19], v[164:167], v[206:209], v[16:19]
	v_mfma_f32_16x16x32_bf16 v[8:11], v[178:181], v[206:209], v[8:11]
	v_mfma_f32_16x16x32_bf16 v[4:7], v[164:167], v[214:217], v[4:7]
	v_mfma_f32_16x16x32_bf16 v[0:3], v[178:181], v[214:217], v[0:3]
	v_mfma_f32_16x16x32_bf16 v[48:51], v[174:177], v[190:193], v[48:51]
	v_mfma_f32_16x16x32_bf16 v[40:43], v[182:185], v[190:193], v[40:43]
	v_mfma_f32_16x16x32_bf16 v[32:35], v[174:177], v[202:205], v[32:35]
	v_mfma_f32_16x16x32_bf16 v[24:27], v[182:185], v[202:205], v[24:27]
	v_mfma_f32_16x16x32_bf16 v[16:19], v[174:177], v[210:213], v[16:19]
	v_mfma_f32_16x16x32_bf16 v[8:11], v[182:185], v[210:213], v[8:11]
	v_mfma_f32_16x16x32_bf16 v[4:7], v[174:177], v[218:221], v[4:7]
	v_mfma_f32_16x16x32_bf16 v[0:3], v[182:185], v[218:221], v[0:3]
	s_barrier
	s_add_i32 s84, s84, 2
	s_add_u32 s44, s44, 0x100
	s_addc_u32 s45, s45, 0
	s_add_u32 s43, s43, 0x100
	s_addc_u32 s83, s83, 0
	s_cmp_gt_u32 s84, 13
	s_cbranch_scc0 .LBB0_177
	s_and_b64 vcc, exec, s[18:19]
	s_cbranch_vccz .LBB0_180
	s_barrier

.LBB0_497:
	s_waitcnt lgkmcnt(0)
	ds_read_b128 v[0:3], v147
	ds_read_b128 v[4:7], v147 offset:1024
	ds_read_b128 v[8:11], v147 offset:2048
	ds_read_b128 v[12:15], v147 offset:3072
	ds_read_b128 v[16:19], v148
	ds_read_b128 v[20:23], v148 offset:1024
	ds_read_b128 v[24:27], v148 offset:2048
	ds_read_b128 v[28:31], v148 offset:3072
	s_ashr_i32 s49, s48, 31
	s_lshl_b64 s[50:51], s[48:49], 17
	s_add_u32 s50, s68, s50
	s_addc_u32 s51, s69, s51
	s_and_b64 s[52:53], s[8:9], exec
	s_cselect_b32 s65, s51, s59
	s_cselect_b32 s64, s50, s58
	s_ashr_i32 s45, s44, 31
	s_lshl_b64 s[52:53], s[44:45], 17
	s_add_u32 s52, s72, s52
	s_addc_u32 s53, s73, s53
	s_and_b64 s[62:63], s[8:9], exec
	s_cselect_b32 s63, s53, s61
	s_cselect_b32 s62, s52, s60
	s_add_u32 s92, s58, 0x10080
	s_addc_u32 s93, s59, 0
	s_add_i32 s94, s81, 0xc000
	v_lshl_add_u64 v[64:65], s[92:93], 0, v[128:129]
	s_mov_b32 m0, s94
	s_add_i32 s45, s81, 0xe000
	ds_read_b128 v[32:35], v149
	ds_read_b128 v[36:39], v149 offset:1024
	ds_read_b128 v[40:43], v149 offset:2048
	ds_read_b128 v[44:47], v149 offset:3072
	ds_read_b128 v[48:51], v149 offset:4096
	ds_read_b128 v[52:55], v149 offset:5120
	ds_read_b128 v[56:59], v149 offset:6144
	ds_read_b128 v[60:63], v149 offset:7168
	global_load_lds_dwordx4 v[64:65], off
	s_mov_b32 m0, s45
	v_lshl_add_u64 v[64:65], s[92:93], 0, v[132:133]
	global_load_lds_dwordx4 v[64:65], off
	s_waitcnt vmcnt(8)
	s_waitcnt lgkmcnt(0)
	s_barrier
	s_waitcnt lgkmcnt(0)
	v_mfma_f32_16x16x32_bf16 v[64:67], v[0:3], v[32:35], 0
	v_mfma_f32_16x16x32_bf16 v[68:71], v[8:11], v[32:35], 0
	v_mfma_f32_16x16x32_bf16 v[72:75], v[0:3], v[40:43], 0
	v_mfma_f32_16x16x32_bf16 v[76:79], v[8:11], v[40:43], 0
	v_mfma_f32_16x16x32_bf16 v[80:83], v[0:3], v[48:51], 0
	v_mfma_f32_16x16x32_bf16 v[84:87], v[8:11], v[48:51], 0
	v_mfma_f32_16x16x32_bf16 v[88:91], v[0:3], v[56:59], 0
	v_mfma_f32_16x16x32_bf16 v[92:95], v[8:11], v[56:59], 0
	v_mfma_f32_16x16x32_bf16 v[64:67], v[4:7], v[36:39], v[64:67]
	v_mfma_f32_16x16x32_bf16 v[68:71], v[12:15], v[36:39], v[68:71]
	v_mfma_f32_16x16x32_bf16 v[72:75], v[4:7], v[44:47], v[72:75]
	v_mfma_f32_16x16x32_bf16 v[76:79], v[12:15], v[44:47], v[76:79]
	v_mfma_f32_16x16x32_bf16 v[80:83], v[4:7], v[52:55], v[80:83]
	v_mfma_f32_16x16x32_bf16 v[84:87], v[12:15], v[52:55], v[84:87]
	v_mfma_f32_16x16x32_bf16 v[88:91], v[4:7], v[60:63], v[88:91]
	v_mfma_f32_16x16x32_bf16 v[92:95], v[12:15], v[60:63], v[92:95]
	v_mfma_f32_16x16x32_bf16 v[96:99], v[16:19], v[32:35], 0
	v_mfma_f32_16x16x32_bf16 v[32:35], v[24:27], v[32:35], 0
	v_mfma_f32_16x16x32_bf16 v[96:99], v[20:23], v[36:39], v[96:99]
	v_mfma_f32_16x16x32_bf16 v[32:35], v[28:31], v[36:39], v[32:35]
	v_mfma_f32_16x16x32_bf16 v[36:39], v[16:19], v[40:43], 0
	v_mfma_f32_16x16x32_bf16 v[40:43], v[24:27], v[40:43], 0
	v_mfma_f32_16x16x32_bf16 v[36:39], v[20:23], v[44:47], v[36:39]
	v_mfma_f32_16x16x32_bf16 v[40:43], v[28:31], v[44:47], v[40:43]
	v_mfma_f32_16x16x32_bf16 v[44:47], v[16:19], v[48:51], 0
	v_mfma_f32_16x16x32_bf16 v[48:51], v[24:27], v[48:51], 0
	v_mfma_f32_16x16x32_bf16 v[44:47], v[20:23], v[52:55], v[44:47]
	v_mfma_f32_16x16x32_bf16 v[48:51], v[28:31], v[52:55], v[48:51]
	v_mfma_f32_16x16x32_bf16 v[52:55], v[16:19], v[56:59], 0
	v_mfma_f32_16x16x32_bf16 v[56:59], v[24:27], v[56:59], 0
	v_mfma_f32_16x16x32_bf16 v[52:55], v[20:23], v[60:63], v[52:55]
	v_mfma_f32_16x16x32_bf16 v[56:59], v[28:31], v[60:63], v[56:59]
	s_barrier
	s_add_i32 s92, s88, s80
	v_lshl_add_u64 v[212:213], s[60:61], 0, v[130:131]
	s_add_i32 s49, s92, 0x2000
	v_lshl_add_u64 v[140:141], v[212:213], 0, s[38:39]
	s_mov_b32 m0, s92
	v_lshl_add_u64 v[214:215], s[60:61], 0, v[134:135]
	s_add_u32 s96, s60, 0x10100
	ds_read_b128 v[60:63], v149 offset:16384
	ds_read_b128 v[100:103], v149 offset:17408
	ds_read_b128 v[104:107], v149 offset:18432
	ds_read_b128 v[108:111], v149 offset:19456
	ds_read_b128 v[112:115], v149 offset:20480
	ds_read_b128 v[116:119], v149 offset:21504
	ds_read_b128 v[120:123], v149 offset:22528
	ds_read_b128 v[124:127], v149 offset:23552
	global_load_lds_dwordx4 v[140:141], off
	v_lshl_add_u64 v[140:141], v[214:215], 0, s[38:39]
	s_mov_b32 m0, s49
	s_addc_u32 s97, s61, 0
	s_add_i32 s55, s89, s80
	global_load_lds_dwordx4 v[140:141], off
	v_lshl_add_u64 v[140:141], s[96:97], 0, v[130:131]
	s_mov_b32 m0, s55
	s_add_i32 s57, s55, 0x2000
	global_load_lds_dwordx4 v[140:141], off
	v_lshl_add_u64 v[140:141], s[96:97], 0, v[134:135]
	s_mov_b32 m0, s57
	v_lshl_add_u64 v[216:217], s[58:59], 0, v[128:129]
	global_load_lds_dwordx4 v[140:141], off
	v_lshl_add_u64 v[140:141], v[216:217], 0, s[38:39]
	s_mov_b32 m0, s81
	v_lshl_add_u64 v[218:219], s[58:59], 0, v[132:133]
	global_load_lds_dwordx4 v[140:141], off
	s_mov_b32 m0, s82
	v_lshl_add_u64 v[140:141], v[218:219], 0, s[38:39]
	global_load_lds_dwordx4 v[140:141], off
	s_waitcnt vmcnt(8)
	s_waitcnt lgkmcnt(0)
	s_barrier
	s_waitcnt lgkmcnt(0)
	v_mfma_f32_16x16x32_bf16 v[140:143], v[0:3], v[60:63], 0
	v_mfma_f32_16x16x32_bf16 v[156:159], v[0:3], v[104:107], 0
	v_mfma_f32_16x16x32_bf16 v[164:167], v[0:3], v[112:115], 0
	v_mfma_f32_16x16x32_bf16 v[0:3], v[0:3], v[120:123], 0
	v_mfma_f32_16x16x32_bf16 v[140:143], v[4:7], v[100:103], v[140:143]
	v_mfma_f32_16x16x32_bf16 v[156:159], v[4:7], v[108:111], v[156:159]
	v_mfma_f32_16x16x32_bf16 v[164:167], v[4:7], v[116:119], v[164:167]
	v_mfma_f32_16x16x32_bf16 v[0:3], v[4:7], v[124:127], v[0:3]
	v_mfma_f32_16x16x32_bf16 v[4:7], v[8:11], v[120:123], 0
	v_mfma_f32_16x16x32_bf16 v[152:155], v[8:11], v[60:63], 0
	v_mfma_f32_16x16x32_bf16 v[160:163], v[8:11], v[104:107], 0
	v_mfma_f32_16x16x32_bf16 v[168:171], v[8:11], v[112:115], 0
	v_mfma_f32_16x16x32_bf16 v[4:7], v[12:15], v[124:127], v[4:7]
	v_mfma_f32_16x16x32_bf16 v[152:155], v[12:15], v[100:103], v[152:155]
	v_mfma_f32_16x16x32_bf16 v[160:163], v[12:15], v[108:111], v[160:163]
	v_mfma_f32_16x16x32_bf16 v[168:171], v[12:15], v[116:119], v[168:171]
	v_mfma_f32_16x16x32_bf16 v[8:11], v[16:19], v[60:63], 0
	v_mfma_f32_16x16x32_bf16 v[12:15], v[24:27], v[60:63], 0
	v_mfma_f32_16x16x32_bf16 v[8:11], v[20:23], v[100:103], v[8:11]
	v_mfma_f32_16x16x32_bf16 v[12:15], v[28:31], v[100:103], v[12:15]
	v_mfma_f32_16x16x32_bf16 v[60:63], v[16:19], v[104:107], 0
	v_mfma_f32_16x16x32_bf16 v[100:103], v[24:27], v[104:107], 0
	v_mfma_f32_16x16x32_bf16 v[104:107], v[16:19], v[112:115], 0
	v_mfma_f32_16x16x32_bf16 v[16:19], v[16:19], v[120:123], 0
	v_mfma_f32_16x16x32_bf16 v[60:63], v[20:23], v[108:111], v[60:63]
	v_mfma_f32_16x16x32_bf16 v[100:103], v[28:31], v[108:111], v[100:103]
	v_mfma_f32_16x16x32_bf16 v[104:107], v[20:23], v[116:119], v[104:107]
	v_mfma_f32_16x16x32_bf16 v[108:111], v[24:27], v[112:115], 0
	v_mfma_f32_16x16x32_bf16 v[16:19], v[20:23], v[124:127], v[16:19]
	v_mfma_f32_16x16x32_bf16 v[20:23], v[24:27], v[120:123], 0
	s_add_i32 s95, 0, 0x18000
	s_add_i32 vcc_lo, 0, 0x1c000
	v_add_u32_e32 v151, s95, v145
	v_add_u32_e32 v224, vcc_lo, v145
	v_mfma_f32_16x16x32_bf16 v[108:111], v[28:31], v[116:119], v[108:111]
	v_mfma_f32_16x16x32_bf16 v[20:23], v[28:31], v[124:127], v[20:23]
	s_barrier
	ds_read_b128 v[24:27], v151
	ds_read_b128 v[28:31], v151 offset:1024
	ds_read_b128 v[112:115], v151 offset:2048
	ds_read_b128 v[116:119], v151 offset:3072
	ds_read_b128 v[120:123], v224
	ds_read_b128 v[124:127], v224 offset:1024
	ds_read_b128 v[172:175], v224 offset:2048
	ds_read_b128 v[176:179], v224 offset:3072
	s_add_u32 s96, s58, 0x10100
	s_addc_u32 s97, s59, 0
	s_mov_b32 m0, s83
	v_lshl_add_u64 v[220:221], s[96:97], 0, v[128:129]
	ds_read_b128 v[180:183], v149 offset:32768
	ds_read_b128 v[184:187], v149 offset:33792
	ds_read_b128 v[188:191], v149 offset:34816
	ds_read_b128 v[192:195], v149 offset:35840
	ds_read_b128 v[196:199], v149 offset:36864
	ds_read_b128 v[200:203], v149 offset:37888
	ds_read_b128 v[204:207], v149 offset:38912
	ds_read_b128 v[208:211], v149 offset:39936
	global_load_lds_dwordx4 v[220:221], off
	s_mov_b32 m0, s84
	v_lshl_add_u64 v[220:221], s[96:97], 0, v[132:133]
	global_load_lds_dwordx4 v[220:221], off
	s_waitcnt vmcnt(8)
	s_waitcnt lgkmcnt(0)
	s_barrier
	s_waitcnt lgkmcnt(0)
	v_mfma_f32_16x16x32_bf16 v[64:67], v[24:27], v[180:183], v[64:67]
	v_mfma_f32_16x16x32_bf16 v[68:71], v[112:115], v[180:183], v[68:71]
	v_mfma_f32_16x16x32_bf16 v[72:75], v[24:27], v[188:191], v[72:75]
	v_mfma_f32_16x16x32_bf16 v[76:79], v[112:115], v[188:191], v[76:79]
	v_mfma_f32_16x16x32_bf16 v[80:83], v[24:27], v[196:199], v[80:83]
	v_mfma_f32_16x16x32_bf16 v[84:87], v[112:115], v[196:199], v[84:87]
	v_mfma_f32_16x16x32_bf16 v[88:91], v[24:27], v[204:207], v[88:91]
	v_mfma_f32_16x16x32_bf16 v[92:95], v[112:115], v[204:207], v[92:95]
	v_mfma_f32_16x16x32_bf16 v[64:67], v[28:31], v[184:187], v[64:67]
	v_mfma_f32_16x16x32_bf16 v[68:71], v[116:119], v[184:187], v[68:71]
	v_mfma_f32_16x16x32_bf16 v[72:75], v[28:31], v[192:195], v[72:75]
	v_mfma_f32_16x16x32_bf16 v[76:79], v[116:119], v[192:195], v[76:79]
	v_mfma_f32_16x16x32_bf16 v[80:83], v[28:31], v[200:203], v[80:83]
	v_mfma_f32_16x16x32_bf16 v[84:87], v[116:119], v[200:203], v[84:87]
	v_mfma_f32_16x16x32_bf16 v[88:91], v[28:31], v[208:211], v[88:91]
	v_mfma_f32_16x16x32_bf16 v[92:95], v[116:119], v[208:211], v[92:95]
	v_mfma_f32_16x16x32_bf16 v[96:99], v[120:123], v[180:183], v[96:99]
	v_mfma_f32_16x16x32_bf16 v[32:35], v[172:175], v[180:183], v[32:35]
	v_mfma_f32_16x16x32_bf16 v[36:39], v[120:123], v[188:191], v[36:39]
	v_mfma_f32_16x16x32_bf16 v[40:43], v[172:175], v[188:191], v[40:43]
	v_mfma_f32_16x16x32_bf16 v[44:47], v[120:123], v[196:199], v[44:47]
	v_mfma_f32_16x16x32_bf16 v[48:51], v[172:175], v[196:199], v[48:51]
	v_mfma_f32_16x16x32_bf16 v[52:55], v[120:123], v[204:207], v[52:55]
	v_mfma_f32_16x16x32_bf16 v[56:59], v[172:175], v[204:207], v[56:59]
	v_mfma_f32_16x16x32_bf16 v[96:99], v[124:127], v[184:187], v[96:99]
	v_mfma_f32_16x16x32_bf16 v[32:35], v[176:179], v[184:187], v[32:35]
	v_mfma_f32_16x16x32_bf16 v[36:39], v[124:127], v[192:195], v[36:39]
	v_mfma_f32_16x16x32_bf16 v[40:43], v[176:179], v[192:195], v[40:43]
	v_mfma_f32_16x16x32_bf16 v[44:47], v[124:127], v[200:203], v[44:47]
	v_mfma_f32_16x16x32_bf16 v[48:51], v[176:179], v[200:203], v[48:51]
	v_mfma_f32_16x16x32_bf16 v[52:55], v[124:127], v[208:211], v[52:55]
	v_mfma_f32_16x16x32_bf16 v[56:59], v[176:179], v[208:211], v[56:59]
	s_barrier
	s_add_i32 s95, s95, s80
	s_add_i32 s93, s95, 0x2000
	v_lshl_add_u64 v[212:213], v[212:213], 0, s[40:41]
	s_mov_b32 m0, s95
	s_add_u32 s96, s60, 0x10180
	ds_read_b128 v[180:183], v149 offset:49152
	ds_read_b128 v[184:187], v149 offset:50176
	ds_read_b128 v[188:191], v149 offset:51200
	ds_read_b128 v[192:195], v149 offset:52224
	ds_read_b128 v[196:199], v149 offset:53248
	ds_read_b128 v[200:203], v149 offset:54272
	ds_read_b128 v[204:207], v149 offset:55296
	ds_read_b128 v[208:211], v149 offset:56320
	global_load_lds_dwordx4 v[212:213], off
	v_lshl_add_u64 v[212:213], v[214:215], 0, s[40:41]
	s_mov_b32 m0, s93
	s_addc_u32 s97, s61, 0
	s_add_i32 s60, vcc_lo, s80
	global_load_lds_dwordx4 v[212:213], off
	v_lshl_add_u64 v[212:213], s[96:97], 0, v[130:131]
	s_mov_b32 m0, s60
	s_add_i32 s61, s60, 0x2000
	global_load_lds_dwordx4 v[212:213], off
	s_mov_b32 m0, s61
	v_lshl_add_u64 v[212:213], s[96:97], 0, v[134:135]
	global_load_lds_dwordx4 v[212:213], off
	s_mov_b32 m0, s86
	v_lshl_add_u64 v[212:213], v[216:217], 0, s[40:41]
	global_load_lds_dwordx4 v[212:213], off
	s_mov_b32 m0, s87
	v_lshl_add_u64 v[212:213], v[218:219], 0, s[40:41]
	global_load_lds_dwordx4 v[212:213], off
	s_waitcnt vmcnt(8)
	s_waitcnt lgkmcnt(0)
	s_barrier
	s_waitcnt lgkmcnt(0)
	v_mfma_f32_16x16x32_bf16 v[0:3], v[24:27], v[204:207], v[0:3]
	v_mfma_f32_16x16x32_bf16 v[4:7], v[112:115], v[204:207], v[4:7]
	v_mfma_f32_16x16x32_bf16 v[140:143], v[24:27], v[180:183], v[140:143]
	v_mfma_f32_16x16x32_bf16 v[152:155], v[112:115], v[180:183], v[152:155]
	v_mfma_f32_16x16x32_bf16 v[156:159], v[24:27], v[188:191], v[156:159]
	v_mfma_f32_16x16x32_bf16 v[160:163], v[112:115], v[188:191], v[160:163]
	v_mfma_f32_16x16x32_bf16 v[164:167], v[24:27], v[196:199], v[164:167]
	v_mfma_f32_16x16x32_bf16 v[168:171], v[112:115], v[196:199], v[168:171]
	v_mfma_f32_16x16x32_bf16 v[0:3], v[28:31], v[208:211], v[0:3]
	v_mfma_f32_16x16x32_bf16 v[4:7], v[116:119], v[208:211], v[4:7]
	v_mfma_f32_16x16x32_bf16 v[140:143], v[28:31], v[184:187], v[140:143]
	v_mfma_f32_16x16x32_bf16 v[152:155], v[116:119], v[184:187], v[152:155]
	v_mfma_f32_16x16x32_bf16 v[156:159], v[28:31], v[192:195], v[156:159]
	v_mfma_f32_16x16x32_bf16 v[160:163], v[116:119], v[192:195], v[160:163]
	v_mfma_f32_16x16x32_bf16 v[164:167], v[28:31], v[200:203], v[164:167]
	v_mfma_f32_16x16x32_bf16 v[168:171], v[116:119], v[200:203], v[168:171]
	v_mfma_f32_16x16x32_bf16 v[8:11], v[120:123], v[180:183], v[8:11]
	v_mfma_f32_16x16x32_bf16 v[12:15], v[172:175], v[180:183], v[12:15]
	v_mfma_f32_16x16x32_bf16 v[24:27], v[120:123], v[188:191], v[60:63]
	v_mfma_f32_16x16x32_bf16 v[28:31], v[172:175], v[188:191], v[100:103]
	v_mfma_f32_16x16x32_bf16 v[60:63], v[120:123], v[196:199], v[104:107]
	v_mfma_f32_16x16x32_bf16 v[100:103], v[172:175], v[196:199], v[108:111]
	v_mfma_f32_16x16x32_bf16 v[16:19], v[120:123], v[204:207], v[16:19]
	v_mfma_f32_16x16x32_bf16 v[20:23], v[172:175], v[204:207], v[20:23]
	v_mfma_f32_16x16x32_bf16 v[8:11], v[124:127], v[184:187], v[8:11]
	v_mfma_f32_16x16x32_bf16 v[12:15], v[176:179], v[184:187], v[12:15]
	v_mfma_f32_16x16x32_bf16 v[24:27], v[124:127], v[192:195], v[24:27]
	v_mfma_f32_16x16x32_bf16 v[28:31], v[176:179], v[192:195], v[28:31]
	v_mfma_f32_16x16x32_bf16 v[60:63], v[124:127], v[200:203], v[60:63]
	v_mfma_f32_16x16x32_bf16 v[100:103], v[176:179], v[200:203], v[100:103]
	v_mfma_f32_16x16x32_bf16 v[16:19], v[124:127], v[208:211], v[16:19]
	v_mfma_f32_16x16x32_bf16 v[20:23], v[176:179], v[208:211], v[20:23]
	s_barrier
	ds_read_b128 v[104:107], v147
	ds_read_b128 v[108:111], v147 offset:1024
	ds_read_b128 v[112:115], v147 offset:2048
	ds_read_b128 v[116:119], v147 offset:3072
	ds_read_b128 v[120:123], v148
	ds_read_b128 v[124:127], v148 offset:1024
	ds_read_b128 v[172:175], v148 offset:2048
	ds_read_b128 v[176:179], v148 offset:3072
	s_add_u32 s58, s58, 0x10180
	s_addc_u32 s59, s59, 0
	s_mov_b32 m0, s94
	v_lshl_add_u64 v[212:213], s[58:59], 0, v[128:129]
	ds_read_b128 v[180:183], v149
	ds_read_b128 v[184:187], v149 offset:1024
	ds_read_b128 v[188:191], v149 offset:2048
	ds_read_b128 v[192:195], v149 offset:3072
	ds_read_b128 v[196:199], v149 offset:4096
	ds_read_b128 v[200:203], v149 offset:5120
	ds_read_b128 v[204:207], v149 offset:6144
	ds_read_b128 v[208:211], v149 offset:7168
	global_load_lds_dwordx4 v[212:213], off
	s_mov_b32 m0, s45
	v_lshl_add_u64 v[212:213], s[58:59], 0, v[132:133]
	global_load_lds_dwordx4 v[212:213], off
	s_waitcnt vmcnt(8)
	s_waitcnt lgkmcnt(0)
	s_barrier
	s_waitcnt lgkmcnt(0)
	v_mfma_f32_16x16x32_bf16 v[64:67], v[104:107], v[180:183], v[64:67]
	v_mfma_f32_16x16x32_bf16 v[68:71], v[112:115], v[180:183], v[68:71]
	v_mfma_f32_16x16x32_bf16 v[72:75], v[104:107], v[188:191], v[72:75]
	v_mfma_f32_16x16x32_bf16 v[76:79], v[112:115], v[188:191], v[76:79]
	v_mfma_f32_16x16x32_bf16 v[80:83], v[104:107], v[196:199], v[80:83]
	v_mfma_f32_16x16x32_bf16 v[84:87], v[112:115], v[196:199], v[84:87]
	v_mfma_f32_16x16x32_bf16 v[88:91], v[104:107], v[204:207], v[88:91]
	v_mfma_f32_16x16x32_bf16 v[64:67], v[108:111], v[184:187], v[64:67]
	v_mfma_f32_16x16x32_bf16 v[68:71], v[116:119], v[184:187], v[68:71]
	v_mfma_f32_16x16x32_bf16 v[72:75], v[108:111], v[192:195], v[72:75]
	v_mfma_f32_16x16x32_bf16 v[76:79], v[116:119], v[192:195], v[76:79]
	v_mfma_f32_16x16x32_bf16 v[80:83], v[108:111], v[200:203], v[80:83]
	v_mfma_f32_16x16x32_bf16 v[84:87], v[116:119], v[200:203], v[84:87]
	v_mfma_f32_16x16x32_bf16 v[212:215], v[108:111], v[208:211], v[88:91]
	v_mfma_f32_16x16x32_bf16 v[88:91], v[112:115], v[204:207], v[92:95]
	v_mfma_f32_16x16x32_bf16 v[216:219], v[116:119], v[208:211], v[88:91]
	v_mfma_f32_16x16x32_bf16 v[88:91], v[120:123], v[180:183], v[96:99]
	v_mfma_f32_16x16x32_bf16 v[32:35], v[172:175], v[180:183], v[32:35]
	v_mfma_f32_16x16x32_bf16 v[36:39], v[120:123], v[188:191], v[36:39]
	v_mfma_f32_16x16x32_bf16 v[40:43], v[172:175], v[188:191], v[40:43]
	v_mfma_f32_16x16x32_bf16 v[44:47], v[120:123], v[196:199], v[44:47]
	v_mfma_f32_16x16x32_bf16 v[48:51], v[172:175], v[196:199], v[48:51]
	v_mfma_f32_16x16x32_bf16 v[52:55], v[120:123], v[204:207], v[52:55]
	v_mfma_f32_16x16x32_bf16 v[56:59], v[172:175], v[204:207], v[56:59]
	v_mfma_f32_16x16x32_bf16 v[96:99], v[124:127], v[184:187], v[88:91]
	v_mfma_f32_16x16x32_bf16 v[32:35], v[176:179], v[184:187], v[32:35]
	v_mfma_f32_16x16x32_bf16 v[36:39], v[124:127], v[192:195], v[36:39]
	v_mfma_f32_16x16x32_bf16 v[40:43], v[176:179], v[192:195], v[40:43]
	v_mfma_f32_16x16x32_bf16 v[44:47], v[124:127], v[200:203], v[44:47]
	v_mfma_f32_16x16x32_bf16 v[48:51], v[176:179], v[200:203], v[48:51]
	v_mfma_f32_16x16x32_bf16 v[52:55], v[124:127], v[208:211], v[52:55]
	v_mfma_f32_16x16x32_bf16 v[56:59], v[176:179], v[208:211], v[56:59]
	s_barrier
	s_mov_b32 m0, s92
	v_lshl_add_u64 v[244:245], s[62:63], 0, v[130:131]
	s_add_u32 s58, s62, 0x10000
	ds_read_b128 v[88:91], v149 offset:16384
	ds_read_b128 v[92:95], v149 offset:17408
	ds_read_b128 v[180:183], v149 offset:18432
	ds_read_b128 v[184:187], v149 offset:19456
	ds_read_b128 v[188:191], v149 offset:20480
	ds_read_b128 v[192:195], v149 offset:21504
	ds_read_b128 v[196:199], v149 offset:22528
	ds_read_b128 v[200:203], v149 offset:23552
	global_load_lds_dwordx4 v[244:245], off
	v_lshl_add_u64 v[246:247], s[62:63], 0, v[134:135]
	s_mov_b32 m0, s49
	s_addc_u32 s59, s63, 0
	global_load_lds_dwordx4 v[246:247], off
	v_lshl_add_u64 v[204:205], s[58:59], 0, v[130:131]
	s_mov_b32 m0, s55
	v_lshl_add_u64 v[248:249], s[64:65], 0, v[128:129]
	global_load_lds_dwordx4 v[204:205], off
	v_lshl_add_u64 v[204:205], s[58:59], 0, v[134:135]
	s_mov_b32 m0, s57
	v_lshl_add_u64 v[250:251], s[64:65], 0, v[132:133]
	global_load_lds_dwordx4 v[204:205], off
	s_mov_b32 m0, s81
	s_nop 0
	global_load_lds_dwordx4 v[248:249], off
	s_mov_b32 m0, s82
	s_nop 0
	global_load_lds_dwordx4 v[250:251], off
	s_waitcnt vmcnt(8)
	s_waitcnt lgkmcnt(0)
	s_barrier
	s_waitcnt lgkmcnt(0)
	v_mfma_f32_16x16x32_bf16 v[0:3], v[104:107], v[196:199], v[0:3]
	v_mfma_f32_16x16x32_bf16 v[4:7], v[112:115], v[196:199], v[4:7]
	v_mfma_f32_16x16x32_bf16 v[140:143], v[104:107], v[88:91], v[140:143]
	v_mfma_f32_16x16x32_bf16 v[152:155], v[112:115], v[88:91], v[152:155]
	v_mfma_f32_16x16x32_bf16 v[156:159], v[104:107], v[180:183], v[156:159]
	v_mfma_f32_16x16x32_bf16 v[160:163], v[112:115], v[180:183], v[160:163]
	v_mfma_f32_16x16x32_bf16 v[164:167], v[104:107], v[188:191], v[164:167]
	v_mfma_f32_16x16x32_bf16 v[168:171], v[112:115], v[188:191], v[168:171]
	v_mfma_f32_16x16x32_bf16 v[0:3], v[108:111], v[200:203], v[0:3]
	v_mfma_f32_16x16x32_bf16 v[4:7], v[116:119], v[200:203], v[4:7]
	v_mfma_f32_16x16x32_bf16 v[140:143], v[108:111], v[92:95], v[140:143]
	v_mfma_f32_16x16x32_bf16 v[152:155], v[116:119], v[92:95], v[152:155]
	v_mfma_f32_16x16x32_bf16 v[156:159], v[108:111], v[184:187], v[156:159]
	v_mfma_f32_16x16x32_bf16 v[160:163], v[116:119], v[184:187], v[160:163]
	v_mfma_f32_16x16x32_bf16 v[164:167], v[108:111], v[192:195], v[164:167]
	v_mfma_f32_16x16x32_bf16 v[168:171], v[116:119], v[192:195], v[168:171]
	v_mfma_f32_16x16x32_bf16 v[8:11], v[120:123], v[88:91], v[8:11]
	v_mfma_f32_16x16x32_bf16 v[204:207], v[124:127], v[92:95], v[8:11]
	v_mfma_f32_16x16x32_bf16 v[8:11], v[172:175], v[88:91], v[12:15]
	v_mfma_f32_16x16x32_bf16 v[208:211], v[176:179], v[92:95], v[8:11]
	v_mfma_f32_16x16x32_bf16 v[8:11], v[120:123], v[180:183], v[24:27]
	v_mfma_f32_16x16x32_bf16 v[220:223], v[124:127], v[184:187], v[8:11]
	v_mfma_f32_16x16x32_bf16 v[8:11], v[172:175], v[180:183], v[28:31]
	v_mfma_f32_16x16x32_bf16 v[180:183], v[176:179], v[184:187], v[8:11]
	v_mfma_f32_16x16x32_bf16 v[8:11], v[120:123], v[188:191], v[60:63]
	v_mfma_f32_16x16x32_bf16 v[184:187], v[124:127], v[192:195], v[8:11]
	v_mfma_f32_16x16x32_bf16 v[8:11], v[172:175], v[188:191], v[100:103]
	v_mfma_f32_16x16x32_bf16 v[188:191], v[176:179], v[192:195], v[8:11]
	v_mfma_f32_16x16x32_bf16 v[8:11], v[120:123], v[196:199], v[16:19]
	v_mfma_f32_16x16x32_bf16 v[192:195], v[124:127], v[200:203], v[8:11]
	v_mfma_f32_16x16x32_bf16 v[8:11], v[172:175], v[196:199], v[20:23]
	v_mfma_f32_16x16x32_bf16 v[172:175], v[176:179], v[200:203], v[8:11]
	s_barrier
	s_nop 4
	ds_read_b128 v[8:11], v151
	ds_read_b128 v[12:15], v151 offset:1024
	ds_read_b128 v[16:19], v151 offset:2048
	ds_read_b128 v[20:23], v151 offset:3072
	ds_read_b128 v[176:179], v224
	ds_read_b128 v[196:199], v224 offset:1024
	ds_read_b128 v[200:203], v224 offset:2048
	ds_read_b128 v[224:227], v224 offset:3072
	s_add_u32 s58, s64, 0x10000
	s_addc_u32 s59, s65, 0
	s_mov_b32 m0, s83
	v_lshl_add_u64 v[88:89], s[58:59], 0, v[128:129]
	ds_read_b128 v[24:27], v149 offset:32768
	ds_read_b128 v[28:31], v149 offset:33792
	ds_read_b128 v[60:63], v149 offset:34816
	ds_read_b128 v[100:103], v149 offset:35840
	ds_read_b128 v[228:231], v149 offset:36864
	ds_read_b128 v[232:235], v149 offset:37888
	ds_read_b128 v[236:239], v149 offset:38912
	ds_read_b128 v[240:243], v149 offset:39936
	global_load_lds_dwordx4 v[88:89], off
	s_mov_b32 m0, s84
	v_lshl_add_u64 v[88:89], s[58:59], 0, v[132:133]
	global_load_lds_dwordx4 v[88:89], off
	s_waitcnt vmcnt(8)
	s_waitcnt lgkmcnt(0)
	s_barrier
	s_waitcnt lgkmcnt(0)
	v_mfma_f32_16x16x32_bf16 v[64:67], v[8:11], v[24:27], v[64:67]
	v_mfma_f32_16x16x32_bf16 v[120:123], v[12:15], v[28:31], v[64:67]
	v_mfma_f32_16x16x32_bf16 v[64:67], v[16:19], v[24:27], v[68:71]
	v_mfma_f32_16x16x32_bf16 v[124:127], v[20:23], v[28:31], v[64:67]
	v_mfma_f32_16x16x32_bf16 v[64:67], v[8:11], v[60:63], v[72:75]
	v_mfma_f32_16x16x32_bf16 v[104:107], v[12:15], v[100:103], v[64:67]
	v_mfma_f32_16x16x32_bf16 v[64:67], v[16:19], v[60:63], v[76:79]
	v_mfma_f32_16x16x32_bf16 v[108:111], v[20:23], v[100:103], v[64:67]
	v_mfma_f32_16x16x32_bf16 v[64:67], v[8:11], v[228:231], v[80:83]
	v_mfma_f32_16x16x32_bf16 v[88:91], v[12:15], v[232:235], v[64:67]
	v_mfma_f32_16x16x32_bf16 v[64:67], v[16:19], v[228:231], v[84:87]
	v_mfma_f32_16x16x32_bf16 v[92:95], v[20:23], v[232:235], v[64:67]
	v_mfma_f32_16x16x32_bf16 v[64:67], v[8:11], v[236:239], v[212:215]
	v_mfma_f32_16x16x32_bf16 v[72:75], v[12:15], v[240:243], v[64:67]
	v_mfma_f32_16x16x32_bf16 v[64:67], v[16:19], v[236:239], v[216:219]
	v_mfma_f32_16x16x32_bf16 v[76:79], v[20:23], v[240:243], v[64:67]
	v_mfma_f32_16x16x32_bf16 v[64:67], v[176:179], v[24:27], v[96:99]
	v_mfma_f32_16x16x32_bf16 v[24:27], v[200:203], v[24:27], v[32:35]
	v_mfma_f32_16x16x32_bf16 v[116:119], v[224:227], v[28:31], v[24:27]
	v_mfma_f32_16x16x32_bf16 v[24:27], v[176:179], v[60:63], v[36:39]
	v_mfma_f32_16x16x32_bf16 v[96:99], v[196:199], v[100:103], v[24:27]
	v_mfma_f32_16x16x32_bf16 v[24:27], v[200:203], v[60:63], v[40:43]
	v_mfma_f32_16x16x32_bf16 v[100:103], v[224:227], v[100:103], v[24:27]
	v_mfma_f32_16x16x32_bf16 v[24:27], v[176:179], v[228:231], v[44:47]
	v_mfma_f32_16x16x32_bf16 v[80:83], v[196:199], v[232:235], v[24:27]
	v_mfma_f32_16x16x32_bf16 v[24:27], v[200:203], v[228:231], v[48:51]
	v_mfma_f32_16x16x32_bf16 v[84:87], v[224:227], v[232:235], v[24:27]
	v_mfma_f32_16x16x32_bf16 v[24:27], v[176:179], v[236:239], v[52:55]
	v_mfma_f32_16x16x32_bf16 v[112:115], v[196:199], v[28:31], v[64:67]
	v_mfma_f32_16x16x32_bf16 v[64:67], v[196:199], v[240:243], v[24:27]
	v_mfma_f32_16x16x32_bf16 v[24:27], v[200:203], v[236:239], v[56:59]
	v_mfma_f32_16x16x32_bf16 v[68:71], v[224:227], v[240:243], v[24:27]
	s_barrier
	s_mov_b32 m0, s95
	s_nop 3
	v_lshl_add_u64 v[24:25], v[244:245], 0, s[18:19]
	s_add_u32 s58, s62, 0x10080
	ds_read_b128 v[32:35], v149 offset:49152
	ds_read_b128 v[36:39], v149 offset:50176
	ds_read_b128 v[212:215], v149 offset:51200
	ds_read_b128 v[216:219], v149 offset:52224
	ds_read_b128 v[228:231], v149 offset:53248
	ds_read_b128 v[232:235], v149 offset:54272
	ds_read_b128 v[236:239], v149 offset:55296
	ds_read_b128 v[240:243], v149 offset:56320
	global_load_lds_dwordx4 v[24:25], off
	v_lshl_add_u64 v[24:25], v[246:247], 0, s[18:19]
	s_mov_b32 m0, s93
	s_addc_u32 s59, s63, 0
	global_load_lds_dwordx4 v[24:25], off
	s_mov_b32 m0, s60
	v_lshl_add_u64 v[24:25], s[58:59], 0, v[130:131]
	global_load_lds_dwordx4 v[24:25], off
	s_mov_b32 m0, s61
	v_lshl_add_u64 v[24:25], s[58:59], 0, v[134:135]
	global_load_lds_dwordx4 v[24:25], off
	s_mov_b32 m0, s86
	v_lshl_add_u64 v[24:25], v[248:249], 0, s[18:19]
	global_load_lds_dwordx4 v[24:25], off
	s_mov_b32 m0, s87
	v_lshl_add_u64 v[24:25], v[250:251], 0, s[18:19]
	global_load_lds_dwordx4 v[24:25], off
	s_waitcnt vmcnt(8)
	s_waitcnt lgkmcnt(0)
	s_barrier
	s_waitcnt lgkmcnt(0)
	v_mfma_f32_16x16x32_bf16 v[24:27], v[8:11], v[32:35], v[140:143]
	v_mfma_f32_16x16x32_bf16 v[56:59], v[12:15], v[36:39], v[24:27]
	v_mfma_f32_16x16x32_bf16 v[24:27], v[16:19], v[32:35], v[152:155]
	v_mfma_f32_16x16x32_bf16 v[60:63], v[20:23], v[36:39], v[24:27]
	v_mfma_f32_16x16x32_bf16 v[24:27], v[8:11], v[212:215], v[156:159]
	v_mfma_f32_16x16x32_bf16 v[40:43], v[12:15], v[216:219], v[24:27]
	v_mfma_f32_16x16x32_bf16 v[24:27], v[16:19], v[212:215], v[160:163]
	v_mfma_f32_16x16x32_bf16 v[0:3], v[8:11], v[236:239], v[0:3]
	v_mfma_f32_16x16x32_bf16 v[44:47], v[20:23], v[216:219], v[24:27]
	v_mfma_f32_16x16x32_bf16 v[24:27], v[8:11], v[228:231], v[164:167]
	v_mfma_f32_16x16x32_bf16 v[28:31], v[16:19], v[228:231], v[168:171]
	v_mfma_f32_16x16x32_bf16 v[8:11], v[12:15], v[240:243], v[0:3]
	v_mfma_f32_16x16x32_bf16 v[0:3], v[16:19], v[236:239], v[4:7]
	v_mfma_f32_16x16x32_bf16 v[24:27], v[12:15], v[232:235], v[24:27]
	v_mfma_f32_16x16x32_bf16 v[28:31], v[20:23], v[232:235], v[28:31]
	v_mfma_f32_16x16x32_bf16 v[12:15], v[20:23], v[240:243], v[0:3]
	v_mfma_f32_16x16x32_bf16 v[0:3], v[176:179], v[32:35], v[204:207]
	v_mfma_f32_16x16x32_bf16 v[48:51], v[196:199], v[36:39], v[0:3]
	v_mfma_f32_16x16x32_bf16 v[0:3], v[200:203], v[32:35], v[208:211]
	v_mfma_f32_16x16x32_bf16 v[52:55], v[224:227], v[36:39], v[0:3]
	v_mfma_f32_16x16x32_bf16 v[0:3], v[176:179], v[212:215], v[220:223]
	v_mfma_f32_16x16x32_bf16 v[32:35], v[196:199], v[216:219], v[0:3]
	v_mfma_f32_16x16x32_bf16 v[0:3], v[200:203], v[212:215], v[180:183]
	v_mfma_f32_16x16x32_bf16 v[36:39], v[224:227], v[216:219], v[0:3]
	v_mfma_f32_16x16x32_bf16 v[0:3], v[176:179], v[228:231], v[184:187]
	v_mfma_f32_16x16x32_bf16 v[16:19], v[196:199], v[232:235], v[0:3]
	v_mfma_f32_16x16x32_bf16 v[0:3], v[200:203], v[228:231], v[188:191]
	v_mfma_f32_16x16x32_bf16 v[20:23], v[224:227], v[232:235], v[0:3]
	v_mfma_f32_16x16x32_bf16 v[0:3], v[176:179], v[236:239], v[192:195]
	v_mfma_f32_16x16x32_bf16 v[4:7], v[200:203], v[236:239], v[172:175]
	v_mfma_f32_16x16x32_bf16 v[0:3], v[196:199], v[240:243], v[0:3]
	v_mfma_f32_16x16x32_bf16 v[4:7], v[224:227], v[240:243], v[4:7]
	s_barrier
	s_andn2_b64 vcc, exec, s[24:25]
	s_cbranch_vccnz .LBB0_499
	s_barrier

.LBB0_546:
	v_add_u32_e32 v1, s80, v155
	ds_read_b128 v[146:149], v1
	ds_read_b128 v[150:153], v1 offset:1024
	ds_read_b128 v[162:165], v1 offset:2048
	ds_read_b128 v[166:169], v1 offset:3072
	v_add_u32_e32 v1, s81, v155
	ds_read_b128 v[170:173], v1
	ds_read_b128 v[174:177], v1 offset:1024
	ds_read_b128 v[178:181], v1 offset:2048
	ds_read_b128 v[182:185], v1 offset:3072
	s_and_b64 s[56:57], exec, s[56:57]
	s_cselect_b32 s57, s43, s91
	s_cselect_b32 s56, s89, s90
	s_add_u32 s96, s93, 0x40000
	s_addc_u32 s97, s94, 0
	v_lshl_add_u64 v[2:3], s[96:97], 0, v[132:133]
	s_add_i32 m0, s9, 0xc000
	ds_read_b128 v[186:189], v159
	ds_read_b128 v[190:193], v159 offset:1024
	ds_read_b128 v[194:197], v159 offset:2048
	ds_read_b128 v[198:201], v159 offset:3072
	ds_read_b128 v[202:205], v159 offset:4096
	ds_read_b128 v[206:209], v159 offset:5120
	ds_read_b128 v[210:213], v159 offset:6144
	ds_read_b128 v[214:217], v159 offset:7168
	global_load_lds_dwordx4 v[2:3], off
	s_add_i32 m0, s9, 0xe000
	v_lshl_add_u64 v[2:3], s[96:97], 0, v[136:137]
	global_load_lds_dwordx4 v[2:3], off
	s_waitcnt vmcnt(8)
	s_waitcnt lgkmcnt(0)
	s_barrier
	s_waitcnt lgkmcnt(0)
	v_mfma_f32_16x16x32_bf16 v[128:131], v[146:149], v[186:189], v[128:131]
	v_mfma_f32_16x16x32_bf16 v[124:127], v[162:165], v[186:189], v[124:127]
	v_mfma_f32_16x16x32_bf16 v[112:115], v[146:149], v[194:197], v[112:115]
	v_mfma_f32_16x16x32_bf16 v[108:111], v[162:165], v[194:197], v[108:111]
	v_mfma_f32_16x16x32_bf16 v[96:99], v[146:149], v[202:205], v[96:99]
	v_mfma_f32_16x16x32_bf16 v[92:95], v[162:165], v[202:205], v[92:95]
	v_mfma_f32_16x16x32_bf16 v[80:83], v[146:149], v[210:213], v[80:83]
	v_mfma_f32_16x16x32_bf16 v[76:79], v[162:165], v[210:213], v[76:79]
	v_mfma_f32_16x16x32_bf16 v[128:131], v[150:153], v[190:193], v[128:131]
	v_mfma_f32_16x16x32_bf16 v[124:127], v[166:169], v[190:193], v[124:127]
	v_mfma_f32_16x16x32_bf16 v[112:115], v[150:153], v[198:201], v[112:115]
	v_mfma_f32_16x16x32_bf16 v[108:111], v[166:169], v[198:201], v[108:111]
	v_mfma_f32_16x16x32_bf16 v[96:99], v[150:153], v[206:209], v[96:99]
	v_mfma_f32_16x16x32_bf16 v[92:95], v[166:169], v[206:209], v[92:95]
	v_mfma_f32_16x16x32_bf16 v[80:83], v[150:153], v[214:217], v[80:83]
	v_mfma_f32_16x16x32_bf16 v[76:79], v[166:169], v[214:217], v[76:79]
	v_mfma_f32_16x16x32_bf16 v[120:123], v[170:173], v[186:189], v[120:123]
	v_mfma_f32_16x16x32_bf16 v[116:119], v[178:181], v[186:189], v[116:119]
	v_mfma_f32_16x16x32_bf16 v[104:107], v[170:173], v[194:197], v[104:107]
	v_mfma_f32_16x16x32_bf16 v[100:103], v[178:181], v[194:197], v[100:103]
	v_mfma_f32_16x16x32_bf16 v[88:91], v[170:173], v[202:205], v[88:91]
	v_mfma_f32_16x16x32_bf16 v[84:87], v[178:181], v[202:205], v[84:87]
	v_mfma_f32_16x16x32_bf16 v[72:75], v[170:173], v[210:213], v[72:75]
	v_mfma_f32_16x16x32_bf16 v[68:71], v[178:181], v[210:213], v[68:71]
	v_mfma_f32_16x16x32_bf16 v[120:123], v[174:177], v[190:193], v[120:123]
	v_mfma_f32_16x16x32_bf16 v[116:119], v[182:185], v[190:193], v[116:119]
	v_mfma_f32_16x16x32_bf16 v[104:107], v[174:177], v[198:201], v[104:107]
	v_mfma_f32_16x16x32_bf16 v[100:103], v[182:185], v[198:201], v[100:103]
	v_mfma_f32_16x16x32_bf16 v[88:91], v[174:177], v[206:209], v[88:91]
	v_mfma_f32_16x16x32_bf16 v[84:87], v[182:185], v[206:209], v[84:87]
	s_add_i32 s14, s80, s0
	v_lshl_add_u64 v[218:219], s[56:57], 0, v[134:135]
	s_mov_b32 m0, s14
	v_mfma_f32_16x16x32_bf16 v[72:75], v[174:177], v[214:217], v[72:75]
	v_mfma_f32_16x16x32_bf16 v[68:71], v[182:185], v[214:217], v[68:71]
	s_barrier
	ds_read_b128 v[186:189], v159 offset:16384
	ds_read_b128 v[190:193], v159 offset:17408
	ds_read_b128 v[194:197], v159 offset:18432
	ds_read_b128 v[198:201], v159 offset:19456
	ds_read_b128 v[202:205], v159 offset:20480
	ds_read_b128 v[206:209], v159 offset:21504
	ds_read_b128 v[210:213], v159 offset:22528
	ds_read_b128 v[214:217], v159 offset:23552
	global_load_lds_dwordx4 v[218:219], off
	s_add_i32 m0, s14, 0x2000
	s_add_u32 s94, s56, 0x80000
	v_lshl_add_u64 v[220:221], s[56:57], 0, v[138:139]
	s_addc_u32 s95, s57, 0
	s_add_i32 s14, s81, s0
	global_load_lds_dwordx4 v[220:221], off
	v_lshl_add_u64 v[2:3], s[94:95], 0, v[134:135]
	s_mov_b32 m0, s14
	v_lshl_add_u64 v[222:223], s[58:59], 0, v[132:133]
	global_load_lds_dwordx4 v[2:3], off
	v_lshl_add_u64 v[2:3], s[94:95], 0, v[138:139]
	s_add_i32 m0, s14, 0x2000
	v_lshl_add_u64 v[224:225], s[58:59], 0, v[136:137]
	global_load_lds_dwordx4 v[2:3], off
	s_mov_b32 m0, s9
	s_nop 0
	global_load_lds_dwordx4 v[222:223], off
	s_mov_b32 m0, s62
	s_nop 0
	global_load_lds_dwordx4 v[224:225], off
	s_waitcnt vmcnt(8)
	s_waitcnt lgkmcnt(0)
	s_barrier
	s_waitcnt lgkmcnt(0)
	v_mfma_f32_16x16x32_bf16 v[64:67], v[146:149], v[186:189], v[64:67]
	v_mfma_f32_16x16x32_bf16 v[60:63], v[162:165], v[186:189], v[60:63]
	v_mfma_f32_16x16x32_bf16 v[48:51], v[146:149], v[194:197], v[48:51]
	v_mfma_f32_16x16x32_bf16 v[44:47], v[162:165], v[194:197], v[44:47]
	v_mfma_f32_16x16x32_bf16 v[32:35], v[146:149], v[202:205], v[32:35]
	v_mfma_f32_16x16x32_bf16 v[28:31], v[162:165], v[202:205], v[28:31]
	v_mfma_f32_16x16x32_bf16 v[16:19], v[146:149], v[210:213], v[16:19]
	v_mfma_f32_16x16x32_bf16 v[12:15], v[162:165], v[210:213], v[12:15]
	v_mfma_f32_16x16x32_bf16 v[64:67], v[150:153], v[190:193], v[64:67]
	v_mfma_f32_16x16x32_bf16 v[60:63], v[166:169], v[190:193], v[60:63]
	v_mfma_f32_16x16x32_bf16 v[48:51], v[150:153], v[198:201], v[48:51]
	v_mfma_f32_16x16x32_bf16 v[44:47], v[166:169], v[198:201], v[44:47]
	v_mfma_f32_16x16x32_bf16 v[32:35], v[150:153], v[206:209], v[32:35]
	v_mfma_f32_16x16x32_bf16 v[28:31], v[166:169], v[206:209], v[28:31]
	v_mfma_f32_16x16x32_bf16 v[16:19], v[150:153], v[214:217], v[16:19]
	v_mfma_f32_16x16x32_bf16 v[12:15], v[166:169], v[214:217], v[12:15]
	v_mfma_f32_16x16x32_bf16 v[56:59], v[170:173], v[186:189], v[56:59]
	v_mfma_f32_16x16x32_bf16 v[52:55], v[178:181], v[186:189], v[52:55]
	v_mfma_f32_16x16x32_bf16 v[40:43], v[170:173], v[194:197], v[40:43]
	v_mfma_f32_16x16x32_bf16 v[36:39], v[178:181], v[194:197], v[36:39]
	v_mfma_f32_16x16x32_bf16 v[24:27], v[170:173], v[202:205], v[24:27]
	v_mfma_f32_16x16x32_bf16 v[20:23], v[178:181], v[202:205], v[20:23]
	v_mfma_f32_16x16x32_bf16 v[8:11], v[170:173], v[210:213], v[8:11]
	v_mfma_f32_16x16x32_bf16 v[2:5], v[178:181], v[210:213], v[4:7]
	v_mfma_f32_16x16x32_bf16 v[56:59], v[174:177], v[190:193], v[56:59]
	v_mfma_f32_16x16x32_bf16 v[52:55], v[182:185], v[190:193], v[52:55]
	v_mfma_f32_16x16x32_bf16 v[40:43], v[174:177], v[198:201], v[40:43]
	v_mfma_f32_16x16x32_bf16 v[36:39], v[182:185], v[198:201], v[36:39]
	v_mfma_f32_16x16x32_bf16 v[24:27], v[174:177], v[206:209], v[24:27]
	v_mfma_f32_16x16x32_bf16 v[20:23], v[182:185], v[206:209], v[20:23]
	s_add_i32 s14, 0, 0x18000
	v_add_u32_e32 v1, s14, v155
	s_add_i32 s93, 0, 0x1c000
	v_mfma_f32_16x16x32_bf16 v[8:11], v[174:177], v[214:217], v[8:11]
	v_mfma_f32_16x16x32_bf16 v[2:5], v[182:185], v[214:217], v[2:5]
	s_barrier
	ds_read_b128 v[146:149], v1
	ds_read_b128 v[150:153], v1 offset:1024
	ds_read_b128 v[162:165], v1 offset:2048
	ds_read_b128 v[166:169], v1 offset:3072
	v_add_u32_e32 v1, s93, v155
	ds_read_b128 v[170:173], v1
	ds_read_b128 v[174:177], v1 offset:1024
	ds_read_b128 v[178:181], v1 offset:2048
	ds_read_b128 v[182:185], v1 offset:3072
	s_add_u32 s58, s58, 0x40000
	s_addc_u32 s59, s59, 0
	s_mov_b32 m0, s63
	v_lshl_add_u64 v[6:7], s[58:59], 0, v[132:133]
	ds_read_b128 v[186:189], v159 offset:32768
	ds_read_b128 v[190:193], v159 offset:33792
	ds_read_b128 v[194:197], v159 offset:34816
	ds_read_b128 v[198:201], v159 offset:35840
	ds_read_b128 v[202:205], v159 offset:36864
	ds_read_b128 v[206:209], v159 offset:37888
	ds_read_b128 v[210:213], v159 offset:38912
	ds_read_b128 v[214:217], v159 offset:39936
	global_load_lds_dwordx4 v[6:7], off
	s_mov_b32 m0, s64
	v_lshl_add_u64 v[6:7], s[58:59], 0, v[136:137]
	global_load_lds_dwordx4 v[6:7], off
	s_waitcnt vmcnt(8)
	s_waitcnt lgkmcnt(0)
	s_barrier
	s_waitcnt lgkmcnt(0)
	v_mfma_f32_16x16x32_bf16 v[128:131], v[146:149], v[186:189], v[128:131]
	v_mfma_f32_16x16x32_bf16 v[124:127], v[162:165], v[186:189], v[124:127]
	v_mfma_f32_16x16x32_bf16 v[112:115], v[146:149], v[194:197], v[112:115]
	v_mfma_f32_16x16x32_bf16 v[108:111], v[162:165], v[194:197], v[108:111]
	v_mfma_f32_16x16x32_bf16 v[96:99], v[146:149], v[202:205], v[96:99]
	v_mfma_f32_16x16x32_bf16 v[92:95], v[162:165], v[202:205], v[92:95]
	v_mfma_f32_16x16x32_bf16 v[80:83], v[146:149], v[210:213], v[80:83]
	v_mfma_f32_16x16x32_bf16 v[76:79], v[162:165], v[210:213], v[76:79]
	v_mfma_f32_16x16x32_bf16 v[128:131], v[150:153], v[190:193], v[128:131]
	v_mfma_f32_16x16x32_bf16 v[124:127], v[166:169], v[190:193], v[124:127]
	v_mfma_f32_16x16x32_bf16 v[112:115], v[150:153], v[198:201], v[112:115]
	v_mfma_f32_16x16x32_bf16 v[108:111], v[166:169], v[198:201], v[108:111]
	v_mfma_f32_16x16x32_bf16 v[96:99], v[150:153], v[206:209], v[96:99]
	v_mfma_f32_16x16x32_bf16 v[92:95], v[166:169], v[206:209], v[92:95]
	v_mfma_f32_16x16x32_bf16 v[80:83], v[150:153], v[214:217], v[80:83]
	v_mfma_f32_16x16x32_bf16 v[76:79], v[166:169], v[214:217], v[76:79]
	v_mfma_f32_16x16x32_bf16 v[120:123], v[170:173], v[186:189], v[120:123]
	v_mfma_f32_16x16x32_bf16 v[116:119], v[178:181], v[186:189], v[116:119]
	v_mfma_f32_16x16x32_bf16 v[104:107], v[170:173], v[194:197], v[104:107]
	v_mfma_f32_16x16x32_bf16 v[100:103], v[178:181], v[194:197], v[100:103]
	v_mfma_f32_16x16x32_bf16 v[88:91], v[170:173], v[202:205], v[88:91]
	v_mfma_f32_16x16x32_bf16 v[84:87], v[178:181], v[202:205], v[84:87]
	v_mfma_f32_16x16x32_bf16 v[72:75], v[170:173], v[210:213], v[72:75]
	v_mfma_f32_16x16x32_bf16 v[68:71], v[178:181], v[210:213], v[68:71]
	v_mfma_f32_16x16x32_bf16 v[120:123], v[174:177], v[190:193], v[120:123]
	v_mfma_f32_16x16x32_bf16 v[116:119], v[182:185], v[190:193], v[116:119]
	v_mfma_f32_16x16x32_bf16 v[104:107], v[174:177], v[198:201], v[104:107]
	v_mfma_f32_16x16x32_bf16 v[100:103], v[182:185], v[198:201], v[100:103]
	v_mfma_f32_16x16x32_bf16 v[88:91], v[174:177], v[206:209], v[88:91]
	v_mfma_f32_16x16x32_bf16 v[84:87], v[182:185], v[206:209], v[84:87]
	s_add_i32 s14, s14, s0
	v_lshl_add_u64 v[6:7], v[218:219], 0, s[24:25]
	s_mov_b32 m0, s14
	v_mfma_f32_16x16x32_bf16 v[72:75], v[174:177], v[214:217], v[72:75]
	v_mfma_f32_16x16x32_bf16 v[68:71], v[182:185], v[214:217], v[68:71]
	s_barrier
	ds_read_b128 v[186:189], v159 offset:49152
	ds_read_b128 v[190:193], v159 offset:50176
	ds_read_b128 v[194:197], v159 offset:51200
	ds_read_b128 v[198:201], v159 offset:52224
	ds_read_b128 v[202:205], v159 offset:53248
	ds_read_b128 v[206:209], v159 offset:54272
	ds_read_b128 v[210:213], v159 offset:55296
	ds_read_b128 v[214:217], v159 offset:56320
	global_load_lds_dwordx4 v[6:7], off
	s_add_i32 m0, s14, 0x2000
	s_add_u32 s56, s56, 0x80080
	v_lshl_add_u64 v[6:7], v[220:221], 0, s[24:25]
	s_addc_u32 s57, s57, 0
	s_add_i32 s14, s93, s0
	global_load_lds_dwordx4 v[6:7], off
	s_mov_b32 m0, s14
	v_lshl_add_u64 v[6:7], s[56:57], 0, v[134:135]
	global_load_lds_dwordx4 v[6:7], off
	s_add_i32 m0, s14, 0x2000
	v_lshl_add_u64 v[6:7], s[56:57], 0, v[138:139]
	global_load_lds_dwordx4 v[6:7], off
	s_mov_b32 m0, s72
	v_lshl_add_u64 v[6:7], v[222:223], 0, s[24:25]
	global_load_lds_dwordx4 v[6:7], off
	s_mov_b32 m0, s73
	v_lshl_add_u64 v[6:7], v[224:225], 0, s[24:25]
	global_load_lds_dwordx4 v[6:7], off
	s_waitcnt vmcnt(8)
	s_waitcnt lgkmcnt(0)
	s_barrier
	s_waitcnt lgkmcnt(0)
	v_mfma_f32_16x16x32_bf16 v[64:67], v[146:149], v[186:189], v[64:67]
	v_mfma_f32_16x16x32_bf16 v[60:63], v[162:165], v[186:189], v[60:63]
	v_mfma_f32_16x16x32_bf16 v[48:51], v[146:149], v[194:197], v[48:51]
	v_mfma_f32_16x16x32_bf16 v[44:47], v[162:165], v[194:197], v[44:47]
	v_mfma_f32_16x16x32_bf16 v[32:35], v[146:149], v[202:205], v[32:35]
	v_mfma_f32_16x16x32_bf16 v[28:31], v[162:165], v[202:205], v[28:31]
	v_mfma_f32_16x16x32_bf16 v[16:19], v[146:149], v[210:213], v[16:19]
	v_mfma_f32_16x16x32_bf16 v[12:15], v[162:165], v[210:213], v[12:15]
	v_mfma_f32_16x16x32_bf16 v[64:67], v[150:153], v[190:193], v[64:67]
	v_mfma_f32_16x16x32_bf16 v[60:63], v[166:169], v[190:193], v[60:63]
	v_mfma_f32_16x16x32_bf16 v[48:51], v[150:153], v[198:201], v[48:51]
	v_mfma_f32_16x16x32_bf16 v[44:47], v[166:169], v[198:201], v[44:47]
	v_mfma_f32_16x16x32_bf16 v[32:35], v[150:153], v[206:209], v[32:35]
	v_mfma_f32_16x16x32_bf16 v[28:31], v[166:169], v[206:209], v[28:31]
	v_mfma_f32_16x16x32_bf16 v[16:19], v[150:153], v[214:217], v[16:19]
	v_mfma_f32_16x16x32_bf16 v[12:15], v[166:169], v[214:217], v[12:15]
	v_mfma_f32_16x16x32_bf16 v[56:59], v[170:173], v[186:189], v[56:59]
	v_mfma_f32_16x16x32_bf16 v[52:55], v[178:181], v[186:189], v[52:55]
	v_mfma_f32_16x16x32_bf16 v[40:43], v[170:173], v[194:197], v[40:43]
	v_mfma_f32_16x16x32_bf16 v[36:39], v[178:181], v[194:197], v[36:39]
	v_mfma_f32_16x16x32_bf16 v[24:27], v[170:173], v[202:205], v[24:27]
	v_mfma_f32_16x16x32_bf16 v[20:23], v[178:181], v[202:205], v[20:23]
	v_mfma_f32_16x16x32_bf16 v[6:9], v[170:173], v[210:213], v[8:11]
	v_mfma_f32_16x16x32_bf16 v[2:5], v[178:181], v[210:213], v[2:5]
	v_mfma_f32_16x16x32_bf16 v[56:59], v[174:177], v[190:193], v[56:59]
	v_mfma_f32_16x16x32_bf16 v[52:55], v[182:185], v[190:193], v[52:55]
	v_mfma_f32_16x16x32_bf16 v[40:43], v[174:177], v[198:201], v[40:43]
	v_mfma_f32_16x16x32_bf16 v[36:39], v[182:185], v[198:201], v[36:39]
	v_mfma_f32_16x16x32_bf16 v[24:27], v[174:177], v[206:209], v[24:27]
	v_mfma_f32_16x16x32_bf16 v[20:23], v[182:185], v[206:209], v[20:23]
	v_mfma_f32_16x16x32_bf16 v[8:11], v[174:177], v[214:217], v[6:9]
	v_mfma_f32_16x16x32_bf16 v[4:7], v[182:185], v[214:217], v[2:5]
	s_barrier
	s_add_i32 s14, s92, 2
	s_add_u32 s54, s54, 0x100
	s_addc_u32 s55, s55, 0
	s_add_u32 s90, s90, 0x100
	s_addc_u32 s91, s91, 0
	s_cmp_gt_u32 s92, 29
	s_mov_b32 s92, s14
	s_cbranch_scc1 .LBB0_554

.LBB0_658:
	v_add_u32_e32 v1, s61, v201
	ds_read_b128 v[102:105], v1
	ds_read_b128 v[106:109], v1 offset:1024
	ds_read_b128 v[110:113], v1 offset:2048
	ds_read_b128 v[114:117], v1 offset:3072
	v_add_u32_e32 v1, s62, v201
	ds_read_b128 v[118:121], v1
	ds_read_b128 v[156:159], v1 offset:1024
	ds_read_b128 v[160:163], v1 offset:2048
	ds_read_b128 v[164:167], v1 offset:3072
	s_and_b64 s[48:49], exec, s[48:49]
	s_cselect_b32 s49, s27, s78
	s_cselect_b32 s48, s29, s73
	s_add_u32 s80, s80, 0x40000
	s_addc_u32 s81, s81, 0
	v_lshl_add_u64 v[2:3], s[80:81], 0, v[178:179]
	s_add_i32 m0, s41, 0xc000
	ds_read_b128 v[168:171], v207
	ds_read_b128 v[184:187], v207 offset:1024
	ds_read_b128 v[188:191], v207 offset:2048
	ds_read_b128 v[192:195], v207 offset:3072
	ds_read_b128 v[208:211], v207 offset:4096
	ds_read_b128 v[212:215], v207 offset:5120
	ds_read_b128 v[216:219], v207 offset:6144
	ds_read_b128 v[220:223], v207 offset:7168
	global_load_lds_dwordx4 v[2:3], off
	s_add_i32 m0, s41, 0xe000
	v_lshl_add_u64 v[2:3], s[80:81], 0, v[174:175]
	global_load_lds_dwordx4 v[2:3], off
	s_waitcnt vmcnt(8)
	s_waitcnt lgkmcnt(0)
	s_barrier
	s_waitcnt lgkmcnt(0)
	v_mfma_f32_16x16x32_bf16 v[152:155], v[102:105], v[168:171], v[152:155]
	v_mfma_f32_16x16x32_bf16 v[148:151], v[110:113], v[168:171], v[148:151]
	v_mfma_f32_16x16x32_bf16 v[144:147], v[102:105], v[188:191], v[144:147]
	v_mfma_f32_16x16x32_bf16 v[140:143], v[110:113], v[188:191], v[140:143]
	v_mfma_f32_16x16x32_bf16 v[136:139], v[102:105], v[208:211], v[136:139]
	v_mfma_f32_16x16x32_bf16 v[132:135], v[110:113], v[208:211], v[132:135]
	v_mfma_f32_16x16x32_bf16 v[128:131], v[102:105], v[216:219], v[128:131]
	v_mfma_f32_16x16x32_bf16 v[122:125], v[110:113], v[216:219], v[124:127]
	v_mfma_f32_16x16x32_bf16 v[152:155], v[106:109], v[184:187], v[152:155]
	v_mfma_f32_16x16x32_bf16 v[148:151], v[114:117], v[184:187], v[148:151]
	v_mfma_f32_16x16x32_bf16 v[144:147], v[106:109], v[192:195], v[144:147]
	v_mfma_f32_16x16x32_bf16 v[140:143], v[114:117], v[192:195], v[140:143]
	v_mfma_f32_16x16x32_bf16 v[136:139], v[106:109], v[212:215], v[136:139]
	v_mfma_f32_16x16x32_bf16 v[132:135], v[114:117], v[212:215], v[132:135]
	v_mfma_f32_16x16x32_bf16 v[128:131], v[106:109], v[220:223], v[128:131]
	v_mfma_f32_16x16x32_bf16 v[122:125], v[114:117], v[220:223], v[122:125]
	v_mfma_f32_16x16x32_bf16 v[64:67], v[118:121], v[168:171], v[64:67]
	v_mfma_f32_16x16x32_bf16 v[60:63], v[160:163], v[168:171], v[60:63]
	v_mfma_f32_16x16x32_bf16 v[56:59], v[118:121], v[188:191], v[56:59]
	v_mfma_f32_16x16x32_bf16 v[52:55], v[160:163], v[188:191], v[52:55]
	v_mfma_f32_16x16x32_bf16 v[48:51], v[118:121], v[208:211], v[48:51]
	v_mfma_f32_16x16x32_bf16 v[44:47], v[160:163], v[208:211], v[44:47]
	v_mfma_f32_16x16x32_bf16 v[40:43], v[118:121], v[216:219], v[40:43]
	v_mfma_f32_16x16x32_bf16 v[36:39], v[160:163], v[216:219], v[36:39]
	v_mfma_f32_16x16x32_bf16 v[64:67], v[156:159], v[184:187], v[64:67]
	v_mfma_f32_16x16x32_bf16 v[60:63], v[164:167], v[184:187], v[60:63]
	v_mfma_f32_16x16x32_bf16 v[56:59], v[156:159], v[192:195], v[56:59]
	v_mfma_f32_16x16x32_bf16 v[52:55], v[164:167], v[192:195], v[52:55]
	v_mfma_f32_16x16x32_bf16 v[48:51], v[156:159], v[212:215], v[48:51]
	v_mfma_f32_16x16x32_bf16 v[44:47], v[164:167], v[212:215], v[44:47]
	s_add_i32 s6, s61, s53
	v_lshl_add_u64 v[196:197], s[48:49], 0, v[176:177]
	s_mov_b32 m0, s6
	v_mfma_f32_16x16x32_bf16 v[40:43], v[156:159], v[220:223], v[40:43]
	v_mfma_f32_16x16x32_bf16 v[36:39], v[164:167], v[220:223], v[36:39]
	s_barrier
	ds_read_b128 v[168:171], v207 offset:16384
	ds_read_b128 v[184:187], v207 offset:17408
	ds_read_b128 v[188:191], v207 offset:18432
	ds_read_b128 v[192:195], v207 offset:19456
	ds_read_b128 v[208:211], v207 offset:20480
	ds_read_b128 v[212:215], v207 offset:21504
	ds_read_b128 v[216:219], v207 offset:22528
	ds_read_b128 v[220:223], v207 offset:23552
	global_load_lds_dwordx4 v[196:197], off
	s_add_i32 m0, s6, 0x2000
	s_add_u32 s80, s48, 0x80000
	v_lshl_add_u64 v[224:225], s[48:49], 0, v[172:173]
	s_addc_u32 s81, s49, 0
	s_add_i32 s6, s62, s53
	global_load_lds_dwordx4 v[224:225], off
	v_lshl_add_u64 v[2:3], s[80:81], 0, v[176:177]
	s_mov_b32 m0, s6
	v_lshl_add_u64 v[226:227], s[50:51], 0, v[178:179]
	global_load_lds_dwordx4 v[2:3], off
	v_lshl_add_u64 v[2:3], s[80:81], 0, v[172:173]
	s_add_i32 m0, s6, 0x2000
	v_lshl_add_u64 v[228:229], s[50:51], 0, v[174:175]
	global_load_lds_dwordx4 v[2:3], off
	s_mov_b32 m0, s41
	s_nop 0
	global_load_lds_dwordx4 v[226:227], off
	s_mov_b32 m0, s56
	s_nop 0
	global_load_lds_dwordx4 v[228:229], off
	s_waitcnt vmcnt(8)
	s_waitcnt lgkmcnt(0)
	s_barrier
	s_waitcnt lgkmcnt(0)
	v_mfma_f32_16x16x32_bf16 v[96:99], v[102:105], v[168:171], v[96:99]
	v_mfma_f32_16x16x32_bf16 v[92:95], v[110:113], v[168:171], v[92:95]
	v_mfma_f32_16x16x32_bf16 v[88:91], v[102:105], v[188:191], v[88:91]
	v_mfma_f32_16x16x32_bf16 v[84:87], v[110:113], v[188:191], v[84:87]
	v_mfma_f32_16x16x32_bf16 v[80:83], v[102:105], v[208:211], v[80:83]
	v_mfma_f32_16x16x32_bf16 v[76:79], v[110:113], v[208:211], v[76:79]
	v_mfma_f32_16x16x32_bf16 v[72:75], v[102:105], v[216:219], v[72:75]
	v_mfma_f32_16x16x32_bf16 v[68:71], v[110:113], v[216:219], v[68:71]
	v_mfma_f32_16x16x32_bf16 v[96:99], v[106:109], v[184:187], v[96:99]
	v_mfma_f32_16x16x32_bf16 v[92:95], v[114:117], v[184:187], v[92:95]
	v_mfma_f32_16x16x32_bf16 v[88:91], v[106:109], v[192:195], v[88:91]
	v_mfma_f32_16x16x32_bf16 v[84:87], v[114:117], v[192:195], v[84:87]
	v_mfma_f32_16x16x32_bf16 v[80:83], v[106:109], v[212:215], v[80:83]
	v_mfma_f32_16x16x32_bf16 v[76:79], v[114:117], v[212:215], v[76:79]
	v_mfma_f32_16x16x32_bf16 v[72:75], v[106:109], v[220:223], v[72:75]
	v_mfma_f32_16x16x32_bf16 v[68:71], v[114:117], v[220:223], v[68:71]
	v_mfma_f32_16x16x32_bf16 v[32:35], v[118:121], v[168:171], v[32:35]
	v_mfma_f32_16x16x32_bf16 v[28:31], v[160:163], v[168:171], v[28:31]
	v_mfma_f32_16x16x32_bf16 v[24:27], v[118:121], v[188:191], v[24:27]
	v_mfma_f32_16x16x32_bf16 v[20:23], v[160:163], v[188:191], v[20:23]
	v_mfma_f32_16x16x32_bf16 v[16:19], v[118:121], v[208:211], v[16:19]
	v_mfma_f32_16x16x32_bf16 v[12:15], v[160:163], v[208:211], v[12:15]
	v_mfma_f32_16x16x32_bf16 v[8:11], v[118:121], v[216:219], v[8:11]
	v_mfma_f32_16x16x32_bf16 v[2:5], v[160:163], v[216:219], v[4:7]
	v_mfma_f32_16x16x32_bf16 v[32:35], v[156:159], v[184:187], v[32:35]
	v_mfma_f32_16x16x32_bf16 v[28:31], v[164:167], v[184:187], v[28:31]
	v_mfma_f32_16x16x32_bf16 v[24:27], v[156:159], v[192:195], v[24:27]
	v_mfma_f32_16x16x32_bf16 v[20:23], v[164:167], v[192:195], v[20:23]
	v_mfma_f32_16x16x32_bf16 v[16:19], v[156:159], v[212:215], v[16:19]
	v_mfma_f32_16x16x32_bf16 v[12:15], v[164:167], v[212:215], v[12:15]
	s_add_i32 s6, 0, 0x18000
	v_add_u32_e32 v1, s6, v201
	s_add_i32 s80, 0, 0x1c000
	v_mfma_f32_16x16x32_bf16 v[8:11], v[156:159], v[220:223], v[8:11]
	v_mfma_f32_16x16x32_bf16 v[2:5], v[164:167], v[220:223], v[2:5]
	s_barrier
	ds_read_b128 v[102:105], v1
	ds_read_b128 v[106:109], v1 offset:1024
	ds_read_b128 v[110:113], v1 offset:2048
	ds_read_b128 v[114:117], v1 offset:3072
	v_add_u32_e32 v1, s80, v201
	ds_read_b128 v[118:121], v1
	ds_read_b128 v[156:159], v1 offset:1024
	ds_read_b128 v[160:163], v1 offset:2048
	ds_read_b128 v[164:167], v1 offset:3072
	s_add_u32 s50, s50, 0x40000
	s_addc_u32 s51, s51, 0
	s_mov_b32 m0, s57
	v_lshl_add_u64 v[6:7], s[50:51], 0, v[178:179]
	ds_read_b128 v[168:171], v207 offset:32768
	ds_read_b128 v[184:187], v207 offset:33792
	ds_read_b128 v[188:191], v207 offset:34816
	ds_read_b128 v[192:195], v207 offset:35840
	ds_read_b128 v[208:211], v207 offset:36864
	ds_read_b128 v[212:215], v207 offset:37888
	ds_read_b128 v[216:219], v207 offset:38912
	ds_read_b128 v[220:223], v207 offset:39936
	global_load_lds_dwordx4 v[6:7], off
	s_mov_b32 m0, s58
	v_lshl_add_u64 v[6:7], s[50:51], 0, v[174:175]
	global_load_lds_dwordx4 v[6:7], off
	s_waitcnt vmcnt(8)
	s_waitcnt lgkmcnt(0)
	s_barrier
	s_waitcnt lgkmcnt(0)
	v_mfma_f32_16x16x32_bf16 v[152:155], v[102:105], v[168:171], v[152:155]
	v_mfma_f32_16x16x32_bf16 v[148:151], v[110:113], v[168:171], v[148:151]
	v_mfma_f32_16x16x32_bf16 v[144:147], v[102:105], v[188:191], v[144:147]
	v_mfma_f32_16x16x32_bf16 v[140:143], v[110:113], v[188:191], v[140:143]
	v_mfma_f32_16x16x32_bf16 v[136:139], v[102:105], v[208:211], v[136:139]
	v_mfma_f32_16x16x32_bf16 v[132:135], v[110:113], v[208:211], v[132:135]
	v_mfma_f32_16x16x32_bf16 v[126:129], v[102:105], v[216:219], v[128:131]
	v_mfma_f32_16x16x32_bf16 v[122:125], v[110:113], v[216:219], v[122:125]
	v_mfma_f32_16x16x32_bf16 v[152:155], v[106:109], v[184:187], v[152:155]
	v_mfma_f32_16x16x32_bf16 v[148:151], v[114:117], v[184:187], v[148:151]
	v_mfma_f32_16x16x32_bf16 v[144:147], v[106:109], v[192:195], v[144:147]
	v_mfma_f32_16x16x32_bf16 v[140:143], v[114:117], v[192:195], v[140:143]
	v_mfma_f32_16x16x32_bf16 v[136:139], v[106:109], v[212:215], v[136:139]
	v_mfma_f32_16x16x32_bf16 v[132:135], v[114:117], v[212:215], v[132:135]
	v_mfma_f32_16x16x32_bf16 v[128:131], v[106:109], v[220:223], v[126:129]
	v_mfma_f32_16x16x32_bf16 v[124:127], v[114:117], v[220:223], v[122:125]
	v_mfma_f32_16x16x32_bf16 v[64:67], v[118:121], v[168:171], v[64:67]
	v_mfma_f32_16x16x32_bf16 v[60:63], v[160:163], v[168:171], v[60:63]
	v_mfma_f32_16x16x32_bf16 v[56:59], v[118:121], v[188:191], v[56:59]
	v_mfma_f32_16x16x32_bf16 v[52:55], v[160:163], v[188:191], v[52:55]
	v_mfma_f32_16x16x32_bf16 v[48:51], v[118:121], v[208:211], v[48:51]
	v_mfma_f32_16x16x32_bf16 v[44:47], v[160:163], v[208:211], v[44:47]
	v_mfma_f32_16x16x32_bf16 v[40:43], v[118:121], v[216:219], v[40:43]
	v_mfma_f32_16x16x32_bf16 v[36:39], v[160:163], v[216:219], v[36:39]
	v_mfma_f32_16x16x32_bf16 v[64:67], v[156:159], v[184:187], v[64:67]
	v_mfma_f32_16x16x32_bf16 v[60:63], v[164:167], v[184:187], v[60:63]
	v_mfma_f32_16x16x32_bf16 v[56:59], v[156:159], v[192:195], v[56:59]
	v_mfma_f32_16x16x32_bf16 v[52:55], v[164:167], v[192:195], v[52:55]
	v_mfma_f32_16x16x32_bf16 v[48:51], v[156:159], v[212:215], v[48:51]
	v_mfma_f32_16x16x32_bf16 v[44:47], v[164:167], v[212:215], v[44:47]
	s_add_i32 s6, s6, s53
	v_lshl_add_u64 v[6:7], v[196:197], 0, s[14:15]
	s_mov_b32 m0, s6
	v_mfma_f32_16x16x32_bf16 v[40:43], v[156:159], v[220:223], v[40:43]
	v_mfma_f32_16x16x32_bf16 v[36:39], v[164:167], v[220:223], v[36:39]
	s_barrier
	ds_read_b128 v[168:171], v207 offset:49152
	ds_read_b128 v[184:187], v207 offset:50176
	ds_read_b128 v[188:191], v207 offset:51200
	ds_read_b128 v[192:195], v207 offset:52224
	ds_read_b128 v[208:211], v207 offset:53248
	ds_read_b128 v[212:215], v207 offset:54272
	ds_read_b128 v[216:219], v207 offset:55296
	ds_read_b128 v[220:223], v207 offset:56320
	global_load_lds_dwordx4 v[6:7], off
	s_add_i32 m0, s6, 0x2000
	s_add_u32 s48, s48, 0x80080
	v_lshl_add_u64 v[6:7], v[224:225], 0, s[14:15]
	s_addc_u32 s49, s49, 0
	s_add_i32 s6, s80, s53
	global_load_lds_dwordx4 v[6:7], off
	s_mov_b32 m0, s6
	v_lshl_add_u64 v[6:7], s[48:49], 0, v[176:177]
	global_load_lds_dwordx4 v[6:7], off
	s_add_i32 m0, s6, 0x2000
	v_lshl_add_u64 v[6:7], s[48:49], 0, v[172:173]
	global_load_lds_dwordx4 v[6:7], off
	s_mov_b32 m0, s59
	v_lshl_add_u64 v[6:7], v[226:227], 0, s[14:15]
	global_load_lds_dwordx4 v[6:7], off
	s_mov_b32 m0, s60
	v_lshl_add_u64 v[6:7], v[228:229], 0, s[14:15]
	global_load_lds_dwordx4 v[6:7], off
	s_waitcnt vmcnt(8)
	s_waitcnt lgkmcnt(0)
	s_barrier
	s_waitcnt lgkmcnt(0)
	v_mfma_f32_16x16x32_bf16 v[96:99], v[102:105], v[168:171], v[96:99]
	v_mfma_f32_16x16x32_bf16 v[92:95], v[110:113], v[168:171], v[92:95]
	v_mfma_f32_16x16x32_bf16 v[88:91], v[102:105], v[188:191], v[88:91]
	v_mfma_f32_16x16x32_bf16 v[84:87], v[110:113], v[188:191], v[84:87]
	v_mfma_f32_16x16x32_bf16 v[80:83], v[102:105], v[208:211], v[80:83]
	v_mfma_f32_16x16x32_bf16 v[76:79], v[110:113], v[208:211], v[76:79]
	v_mfma_f32_16x16x32_bf16 v[72:75], v[102:105], v[216:219], v[72:75]
	v_mfma_f32_16x16x32_bf16 v[68:71], v[110:113], v[216:219], v[68:71]
	v_mfma_f32_16x16x32_bf16 v[96:99], v[106:109], v[184:187], v[96:99]
	v_mfma_f32_16x16x32_bf16 v[92:95], v[114:117], v[184:187], v[92:95]
	v_mfma_f32_16x16x32_bf16 v[88:91], v[106:109], v[192:195], v[88:91]
	v_mfma_f32_16x16x32_bf16 v[84:87], v[114:117], v[192:195], v[84:87]
	v_mfma_f32_16x16x32_bf16 v[80:83], v[106:109], v[212:215], v[80:83]
	v_mfma_f32_16x16x32_bf16 v[76:79], v[114:117], v[212:215], v[76:79]
	v_mfma_f32_16x16x32_bf16 v[72:75], v[106:109], v[220:223], v[72:75]
	v_mfma_f32_16x16x32_bf16 v[68:71], v[114:117], v[220:223], v[68:71]
	v_mfma_f32_16x16x32_bf16 v[32:35], v[118:121], v[168:171], v[32:35]
	v_mfma_f32_16x16x32_bf16 v[28:31], v[160:163], v[168:171], v[28:31]
	v_mfma_f32_16x16x32_bf16 v[24:27], v[118:121], v[188:191], v[24:27]
	v_mfma_f32_16x16x32_bf16 v[20:23], v[160:163], v[188:191], v[20:23]
	v_mfma_f32_16x16x32_bf16 v[16:19], v[118:121], v[208:211], v[16:19]
	v_mfma_f32_16x16x32_bf16 v[12:15], v[160:163], v[208:211], v[12:15]
	v_mfma_f32_16x16x32_bf16 v[6:9], v[118:121], v[216:219], v[8:11]
	v_mfma_f32_16x16x32_bf16 v[2:5], v[160:163], v[216:219], v[2:5]
	v_mfma_f32_16x16x32_bf16 v[32:35], v[156:159], v[184:187], v[32:35]
	v_mfma_f32_16x16x32_bf16 v[28:31], v[164:167], v[184:187], v[28:31]
	v_mfma_f32_16x16x32_bf16 v[24:27], v[156:159], v[192:195], v[24:27]
	v_mfma_f32_16x16x32_bf16 v[20:23], v[164:167], v[192:195], v[20:23]
	v_mfma_f32_16x16x32_bf16 v[16:19], v[156:159], v[212:215], v[16:19]
	v_mfma_f32_16x16x32_bf16 v[12:15], v[164:167], v[212:215], v[12:15]
	v_mfma_f32_16x16x32_bf16 v[8:11], v[156:159], v[220:223], v[6:9]
	v_mfma_f32_16x16x32_bf16 v[4:7], v[164:167], v[220:223], v[2:5]
	s_barrier
	s_add_i32 s6, s79, 2
	s_add_u32 s44, s44, 0x100
	s_addc_u32 s45, s45, 0
	s_add_u32 s73, s73, 0x100
	s_addc_u32 s78, s78, 0
	s_cmp_gt_u32 s79, 29
	s_cbranch_scc1 .LBB0_660
	s_mov_b32 s79, s6
	s_cmp_lg_u32 s79, 16
	s_cbranch_scc0 .LBB0_652
	s_branch .LBB0_653
